# attention global units split each 64-key tile between wave halves (64 q rows x 32 keys per wave, half the LDS fragment reads, partial O/l combined via LDS); leaner SwiGLU epilogue with prefetched row
# speedup vs baseline: 1.0277x; 1.0277x over previous
;     __device__ __forceinline__ void prefetch(const Unit& u, int wr, int fr, float (&rsv)[2][4]) const {
;         unsigned lrow = (unsigned)(wr * 64 + fr); asm volatile("" : "+v"(lrow)); const float* rb = rsx + u.pm * BM;
; #pragma unroll
;         for (int ai = 0; ai < 2; ++ai)
; #pragma unroll
;             for (int m = 0; m < 4; ++m) rsv[ai][m] = rb[lrow + (unsigned)(ai * HALF + m * 16)];
;     }
; template <class Epi, class Sched, bool ALIGN_EPI = false, bool SP2 = false>
; __device__ __forceinline__ void gemm_phase(PG8_LAS unsigned char* lds, const Gemm g, const Sched& S, const Epi& E, int tid_in) {
;     ...
; #pragma unroll
;         for (int a = 0; a < 2; ++a)
; #pragma unroll
;             for (int b = 0; b < 2; ++b)
; #pragma unroll
;                 for (int m = 0; m < 4; ++m)
; #pragma unroll
;                     for (int n = 0; n < 2; ++n) acc[a][b][m][n] = (f32x4){0.f, 0.f, 0.f, 0.f};
.LBB0_123:
	s_lshl_b32 s100, s30, 10
	s_add_u32 s100, s57, s100
	s_addc_u32 s101, s58, 0
	v_lshlrev_b32_e32 v3, 2, v129
	global_load_dword v234, v3, s[100:101]
	global_load_dword v235, v3, s[100:101] offset:64
	global_load_dword v236, v3, s[100:101] offset:128
	global_load_dword v237, v3, s[100:101] offset:192
	global_load_dword v245, v3, s[100:101] offset:512
	global_load_dword v247, v3, s[100:101] offset:576
	global_load_dword v252, v3, s[100:101] offset:640
	global_load_dword v253, v3, s[100:101] offset:704
	s_ashr_i32 s25, s24, 31
	s_lshl_b64 s[26:27], s[24:25], 19
	s_add_u32 s26, s45, s26
	s_addc_u32 s27, s48, s27
	s_and_b64 s[28:29], s[36:37], exec
	s_cselect_b32 s25, s27, s39
	s_cselect_b32 s61, s26, s38
	s_ashr_i32 s23, s22, 31
	s_lshl_b64 s[28:29], s[22:23], 19
	s_add_u32 s28, s49, s28
	s_addc_u32 s29, s50, s29
	s_and_b64 s[62:63], s[36:37], exec
	s_cselect_b32 s23, s29, s81
	s_cselect_b32 s62, s28, s80
	s_add_u32 s63, s80, 0x100
	v_mov_b32_e32 v2, 0
	v_lshl_add_u64 v[144:145], s[38:39], 0, v[140:141]
	v_lshl_add_u64 v[146:147], s[38:39], 0, v[142:143]
	s_addc_u32 s64, s81, 0
	s_mov_b32 s65, -2
	s_mov_b64 s[80:81], 0
	v_mov_b32_e32 v3, v2
	v_mov_b32_e32 v4, v2
	v_mov_b32_e32 v5, v2
	v_mov_b32_e32 v10, v2
	v_mov_b32_e32 v11, v2
	v_mov_b32_e32 v12, v2
	v_mov_b32_e32 v13, v2
	v_mov_b32_e32 v18, v2
	v_mov_b32_e32 v19, v2
	v_mov_b32_e32 v20, v2
	v_mov_b32_e32 v21, v2
	v_mov_b32_e32 v26, v2
	v_mov_b32_e32 v27, v2
	v_mov_b32_e32 v28, v2
	v_mov_b32_e32 v29, v2
	v_mov_b32_e32 v34, v2
	v_mov_b32_e32 v35, v2
	v_mov_b32_e32 v36, v2
	v_mov_b32_e32 v37, v2
	v_mov_b32_e32 v42, v2
	v_mov_b32_e32 v43, v2
	v_mov_b32_e32 v44, v2
	v_mov_b32_e32 v45, v2
	v_mov_b32_e32 v50, v2
	v_mov_b32_e32 v51, v2
	v_mov_b32_e32 v52, v2
	v_mov_b32_e32 v53, v2
	v_mov_b32_e32 v58, v2
	v_mov_b32_e32 v59, v2
	v_mov_b32_e32 v60, v2
	v_mov_b32_e32 v61, v2
	v_mov_b32_e32 v6, v2
	v_mov_b32_e32 v7, v2
	v_mov_b32_e32 v8, v2
	v_mov_b32_e32 v9, v2
	v_mov_b32_e32 v14, v2
	v_mov_b32_e32 v15, v2
	v_mov_b32_e32 v16, v2
	v_mov_b32_e32 v17, v2
	v_mov_b32_e32 v22, v2
	v_mov_b32_e32 v23, v2
	v_mov_b32_e32 v24, v2
	v_mov_b32_e32 v25, v2
	v_mov_b32_e32 v30, v2
	v_mov_b32_e32 v31, v2
	v_mov_b32_e32 v32, v2
	v_mov_b32_e32 v33, v2
	v_mov_b32_e32 v38, v2
	v_mov_b32_e32 v39, v2
	v_mov_b32_e32 v40, v2
	v_mov_b32_e32 v41, v2
	v_mov_b32_e32 v46, v2
	v_mov_b32_e32 v47, v2
	v_mov_b32_e32 v48, v2
	v_mov_b32_e32 v49, v2
	v_mov_b32_e32 v54, v2
	v_mov_b32_e32 v55, v2
	v_mov_b32_e32 v56, v2
	v_mov_b32_e32 v57, v2
	v_mov_b32_e32 v62, v2
	v_mov_b32_e32 v63, v2
	v_mov_b32_e32 v64, v2
	v_mov_b32_e32 v65, v2
	v_mov_b32_e32 v66, v2
	v_mov_b32_e32 v67, v2
	v_mov_b32_e32 v68, v2
	v_mov_b32_e32 v69, v2
	v_mov_b32_e32 v74, v2
	v_mov_b32_e32 v75, v2
	v_mov_b32_e32 v76, v2
	v_mov_b32_e32 v77, v2
	v_mov_b32_e32 v82, v2
	v_mov_b32_e32 v83, v2
	v_mov_b32_e32 v84, v2
	v_mov_b32_e32 v85, v2
	v_mov_b32_e32 v90, v2
	v_mov_b32_e32 v91, v2
	v_mov_b32_e32 v92, v2
	v_mov_b32_e32 v93, v2
	v_mov_b32_e32 v98, v2
	v_mov_b32_e32 v99, v2
	v_mov_b32_e32 v100, v2
	v_mov_b32_e32 v101, v2
	v_mov_b32_e32 v106, v2
	v_mov_b32_e32 v107, v2
	v_mov_b32_e32 v108, v2
	v_mov_b32_e32 v109, v2
	v_mov_b32_e32 v114, v2
	v_mov_b32_e32 v115, v2
	v_mov_b32_e32 v116, v2
	v_mov_b32_e32 v117, v2
	v_mov_b32_e32 v122, v2
	v_mov_b32_e32 v123, v2
	v_mov_b32_e32 v124, v2
	v_mov_b32_e32 v125, v2
	v_mov_b32_e32 v70, v2
	v_mov_b32_e32 v71, v2
	v_mov_b32_e32 v72, v2
	v_mov_b32_e32 v73, v2
	v_mov_b32_e32 v78, v2
	v_mov_b32_e32 v79, v2
	v_mov_b32_e32 v80, v2
	v_mov_b32_e32 v81, v2
	v_mov_b32_e32 v86, v2
	v_mov_b32_e32 v87, v2
	v_mov_b32_e32 v88, v2
	v_mov_b32_e32 v89, v2
	v_mov_b32_e32 v94, v2
	v_mov_b32_e32 v95, v2
	v_mov_b32_e32 v96, v2
	v_mov_b32_e32 v97, v2
	v_mov_b32_e32 v102, v2
	v_mov_b32_e32 v103, v2
	v_mov_b32_e32 v104, v2
	v_mov_b32_e32 v105, v2
	v_mov_b32_e32 v110, v2
	v_mov_b32_e32 v111, v2
	v_mov_b32_e32 v112, v2
	v_mov_b32_e32 v113, v2
	v_mov_b32_e32 v118, v2
	v_mov_b32_e32 v119, v2
	v_mov_b32_e32 v120, v2
	v_mov_b32_e32 v121, v2
	v_mov_b32_e32 v130, v2
	v_mov_b32_e32 v131, v2
	v_mov_b32_e32 v132, v2
	v_mov_b32_e32 v133, v2

; __device__ __forceinline__ unsigned cvt_pk_bf16(float lo, float hi) { unsigned r; asm volatile("v_cvt_pk_bf16_f32 %0, %1, %2" : "=v"(r) : "v"(lo), "v"(hi)); return r; }
; __device__ __forceinline__ float silu_mul(float g, float u, float c1, float c2) { const float e = __builtin_amdgcn_exp2f(g * c1); return (g * u) * (c2 * __builtin_amdgcn_rcpf(1.0f + e)); }
;     __device__ __forceinline__ void operator()(const f32x4 (&acc)[2][2][4][2], const Unit& u, int wr, int wc, int fr, int fq) const {
;         const int row0 = u.pm * BM + wr * 64 + fr; const int col0 = u.pn * HALF + wc * 32 + 8 * fq;
;         float rsv[2][4]; prefetch(u, wr, fr, rsv);
; #pragma unroll
;         for (int ai = 0; ai < 2; ++ai)
; #pragma unroll
;             for (int m = 0; m < 4; ++m) { bf16_t* rowp = O + (size_t)(row0 + ai * HALF + m * 16) * ldc + col0;
;                 const float rs = rsv[ai][m], c1 = rs * -1.4426950408889634f, c2 = rs * rs; const f32x4 g0 = acc[ai][0][m][0], g1 = acc[ai][0][m][1], u0 = acc[ai][1][m][0], u1 = acc[ai][1][m][1];
;                 u32x4 w; w.x = cvt_pk_bf16(silu_mul(g0[0], u0[0], c1, c2), silu_mul(g0[1], u0[1], c1, c2)); w.y = cvt_pk_bf16(silu_mul(g0[2], u0[2], c1, c2), silu_mul(g0[3], u0[3], c1, c2));
;                 w.z = cvt_pk_bf16(silu_mul(g1[0], u1[0], c1, c2), silu_mul(g1[1], u1[1], c1, c2)); w.w = cvt_pk_bf16(silu_mul(g1[2], u1[2], c1, c2), silu_mul(g1[3], u1[3], c1, c2));
;                 *(u32x4*)rowp = w; }
.LBB0_127:
	s_lshl_b32 s30, s30, 8
	v_lshl_or_b32 v146, s31, 7, v153
	v_add_u32_e32 v155, s30, v129
	v_ashrrev_i32_e32 v147, 31, v146
	v_mov_b64_e32 v[144:145], s[14:15]
	s_movk_i32 s67, 0x3000
	s_mov_b64 s[84:85], 0x4c00000
	v_mad_i64_i32 v[148:149], s[30:31], v155, s33, v[144:145]
	v_lshlrev_b64 v[146:147], 1, v[146:147]
	s_nop 0
	v_lshl_add_u64 v[148:149], v[148:149], 0, v[146:147]
	s_waitcnt vmcnt(8)
	v_mul_f32_e32 v156, 0xbfb8aa3b, v234
	v_mul_f32_e32 v157, v234, v234
	v_mul_f32_e32 v158, v130, v156
	v_mul_f32_e32 v159, v131, v156
	v_mul_f32_e32 v160, v132, v156
	v_mul_f32_e32 v161, v133, v156
	v_mul_f32_e32 v162, v118, v156
	v_mul_f32_e32 v163, v119, v156
	v_mul_f32_e32 v164, v120, v156
	v_mul_f32_e32 v0, v121, v156
	v_exp_f32_e32 v158, v158
	v_exp_f32_e32 v159, v159
	v_exp_f32_e32 v160, v160
	v_exp_f32_e32 v161, v161
	v_exp_f32_e32 v162, v162
	v_exp_f32_e32 v163, v163
	v_exp_f32_e32 v164, v164
	v_exp_f32_e32 v0, v0
	v_mul_f32_e32 v122, v130, v122
	v_mul_f32_e32 v123, v131, v123
	v_mul_f32_e32 v124, v132, v124
	v_mul_f32_e32 v125, v133, v125
	v_mul_f32_e32 v114, v118, v114
	v_mul_f32_e32 v115, v119, v115
	v_mul_f32_e32 v116, v120, v116
	v_mul_f32_e32 v117, v121, v117
	v_add_f32_e32 v158, 1.0, v158
	v_add_f32_e32 v159, 1.0, v159
	v_add_f32_e32 v160, 1.0, v160
	v_add_f32_e32 v161, 1.0, v161
	v_add_f32_e32 v162, 1.0, v162
	v_add_f32_e32 v163, 1.0, v163
	v_add_f32_e32 v164, 1.0, v164
	v_add_f32_e32 v0, 1.0, v0
	v_rcp_f32_e32 v158, v158
	v_rcp_f32_e32 v159, v159
	v_rcp_f32_e32 v160, v160
	v_rcp_f32_e32 v161, v161
	v_rcp_f32_e32 v162, v162
	v_rcp_f32_e32 v163, v163
	v_rcp_f32_e32 v164, v164
	v_rcp_f32_e32 v0, v0
	v_mul_f32_e32 v158, v157, v158
	v_mul_f32_e32 v159, v157, v159
	v_mul_f32_e32 v160, v157, v160
	v_mul_f32_e32 v161, v157, v161
	v_mul_f32_e32 v162, v157, v162
	v_mul_f32_e32 v163, v157, v163
	v_mul_f32_e32 v164, v157, v164
	v_mul_f32_e32 v0, v157, v0
	v_mul_f32_e32 v130, v122, v158
	v_mul_f32_e32 v131, v123, v159
	v_mul_f32_e32 v132, v124, v160
	v_mul_f32_e32 v133, v125, v161
	v_mul_f32_e32 v118, v114, v162
	v_mul_f32_e32 v119, v115, v163
	v_mul_f32_e32 v120, v116, v164
	v_mul_f32_e32 v121, v117, v0
	v_cvt_pk_bf16_f32 v122, v130, v131
	v_cvt_pk_bf16_f32 v123, v132, v133
	v_cvt_pk_bf16_f32 v124, v118, v119
	v_cvt_pk_bf16_f32 v125, v120, v121
	global_store_dwordx4 v[148:149], v[122:125], off
	v_mul_f32_e32 v156, 0xbfb8aa3b, v235
	v_mul_f32_e32 v157, v235, v235
	v_mul_f32_e32 v158, v110, v156
	v_mul_f32_e32 v159, v111, v156
	v_mul_f32_e32 v160, v112, v156
	v_mul_f32_e32 v161, v113, v156
	v_mul_f32_e32 v162, v102, v156
	v_mul_f32_e32 v163, v103, v156
	v_mul_f32_e32 v164, v104, v156
	v_mul_f32_e32 v0, v105, v156
	v_exp_f32_e32 v158, v158
	v_exp_f32_e32 v159, v159
	v_exp_f32_e32 v160, v160
	v_exp_f32_e32 v161, v161
	v_exp_f32_e32 v162, v162
	v_exp_f32_e32 v163, v163
	v_exp_f32_e32 v164, v164
	v_exp_f32_e32 v0, v0
	v_mul_f32_e32 v106, v110, v106
	v_mul_f32_e32 v107, v111, v107
	v_mul_f32_e32 v108, v112, v108
	v_mul_f32_e32 v109, v113, v109
	v_mul_f32_e32 v98, v102, v98
	v_mul_f32_e32 v99, v103, v99
	v_mul_f32_e32 v100, v104, v100
	v_mul_f32_e32 v101, v105, v101
	v_add_f32_e32 v158, 1.0, v158
	v_add_f32_e32 v159, 1.0, v159
	v_add_f32_e32 v160, 1.0, v160
	v_add_f32_e32 v161, 1.0, v161
	v_add_f32_e32 v162, 1.0, v162
	v_add_f32_e32 v163, 1.0, v163
	v_add_f32_e32 v164, 1.0, v164
	v_add_f32_e32 v0, 1.0, v0
	v_rcp_f32_e32 v158, v158
	v_rcp_f32_e32 v159, v159
	v_rcp_f32_e32 v160, v160
	v_rcp_f32_e32 v161, v161
	v_rcp_f32_e32 v162, v162
	v_rcp_f32_e32 v163, v163
	v_rcp_f32_e32 v164, v164
	v_rcp_f32_e32 v0, v0
	v_mul_f32_e32 v158, v157, v158
	v_mul_f32_e32 v159, v157, v159
	v_mul_f32_e32 v160, v157, v160
	v_mul_f32_e32 v161, v157, v161
	v_mul_f32_e32 v162, v157, v162
	v_mul_f32_e32 v163, v157, v163
	v_mul_f32_e32 v164, v157, v164
	v_mul_f32_e32 v0, v157, v0
	v_mul_f32_e32 v110, v106, v158
	v_mul_f32_e32 v111, v107, v159
	v_mul_f32_e32 v112, v108, v160
	v_mul_f32_e32 v113, v109, v161
	v_mul_f32_e32 v102, v98, v162
	v_mul_f32_e32 v103, v99, v163
	v_mul_f32_e32 v104, v100, v164
	v_mul_f32_e32 v105, v101, v0
	v_cvt_pk_bf16_f32 v106, v110, v111
	v_cvt_pk_bf16_f32 v107, v112, v113
	v_cvt_pk_bf16_f32 v108, v102, v103
	v_cvt_pk_bf16_f32 v109, v104, v105
	s_mov_b64 s[100:101], 0x16000
	v_lshl_add_u64 v[150:151], v[148:149], 0, s[100:101]
	global_store_dwordx4 v[150:151], v[106:109], off
	v_mul_f32_e32 v156, 0xbfb8aa3b, v236
	v_mul_f32_e32 v157, v236, v236
	v_mul_f32_e32 v158, v94, v156
	v_mul_f32_e32 v159, v95, v156
	v_mul_f32_e32 v160, v96, v156
	v_mul_f32_e32 v161, v97, v156
	v_mul_f32_e32 v162, v86, v156
	v_mul_f32_e32 v163, v87, v156
	v_mul_f32_e32 v164, v88, v156
	v_mul_f32_e32 v0, v89, v156
	v_exp_f32_e32 v158, v158
	v_exp_f32_e32 v159, v159
	v_exp_f32_e32 v160, v160
	v_exp_f32_e32 v161, v161
	v_exp_f32_e32 v162, v162
	v_exp_f32_e32 v163, v163
	v_exp_f32_e32 v164, v164
	v_exp_f32_e32 v0, v0
	v_mul_f32_e32 v90, v94, v90
	v_mul_f32_e32 v91, v95, v91
	v_mul_f32_e32 v92, v96, v92
	v_mul_f32_e32 v93, v97, v93
	v_mul_f32_e32 v82, v86, v82
	v_mul_f32_e32 v83, v87, v83
	v_mul_f32_e32 v84, v88, v84
	v_mul_f32_e32 v85, v89, v85
	v_add_f32_e32 v158, 1.0, v158
	v_add_f32_e32 v159, 1.0, v159
	v_add_f32_e32 v160, 1.0, v160
	v_add_f32_e32 v161, 1.0, v161
	v_add_f32_e32 v162, 1.0, v162
	v_add_f32_e32 v163, 1.0, v163
	v_add_f32_e32 v164, 1.0, v164
	v_add_f32_e32 v0, 1.0, v0
	v_rcp_f32_e32 v158, v158
	v_rcp_f32_e32 v159, v159
	v_rcp_f32_e32 v160, v160
	v_rcp_f32_e32 v161, v161
	v_rcp_f32_e32 v162, v162
	v_rcp_f32_e32 v163, v163
	v_rcp_f32_e32 v164, v164
	v_rcp_f32_e32 v0, v0
	v_mul_f32_e32 v158, v157, v158
	v_mul_f32_e32 v159, v157, v159
	v_mul_f32_e32 v160, v157, v160
; __device__ __forceinline__ unsigned cvt_pk_bf16(float lo, float hi) { unsigned r; asm volatile("v_cvt_pk_bf16_f32 %0, %1, %2" : "=v"(r) : "v"(lo), "v"(hi)); return r; }
; __device__ __forceinline__ float silu_mul(float g, float u, float c1, float c2) { const float e = __builtin_amdgcn_exp2f(g * c1); return (g * u) * (c2 * __builtin_amdgcn_rcpf(1.0f + e)); }
;     __device__ __forceinline__ void operator()(const f32x4 (&acc)[2][2][4][2], const Unit& u, int wr, int wc, int fr, int fq) const {
;     ...
;             for (int m = 0; m < 4; ++m) { bf16_t* rowp = O + (size_t)(row0 + ai * HALF + m * 16) * ldc + col0;
;                 const float rs = rsv[ai][m], c1 = rs * -1.4426950408889634f, c2 = rs * rs; const f32x4 g0 = acc[ai][0][m][0], g1 = acc[ai][0][m][1], u0 = acc[ai][1][m][0], u1 = acc[ai][1][m][1];
;                 u32x4 w; w.x = cvt_pk_bf16(silu_mul(g0[0], u0[0], c1, c2), silu_mul(g0[1], u0[1], c1, c2)); w.y = cvt_pk_bf16(silu_mul(g0[2], u0[2], c1, c2), silu_mul(g0[3], u0[3], c1, c2));
;                 w.z = cvt_pk_bf16(silu_mul(g1[0], u1[0], c1, c2), silu_mul(g1[1], u1[1], c1, c2)); w.w = cvt_pk_bf16(silu_mul(g1[2], u1[2], c1, c2), silu_mul(g1[3], u1[3], c1, c2));
;                 *(u32x4*)rowp = w; }
	v_mul_f32_e32 v161, v157, v161
	v_mul_f32_e32 v162, v157, v162
	v_mul_f32_e32 v163, v157, v163
	v_mul_f32_e32 v164, v157, v164
	v_mul_f32_e32 v0, v157, v0
	v_mul_f32_e32 v94, v90, v158
	v_mul_f32_e32 v95, v91, v159
	v_mul_f32_e32 v96, v92, v160
	v_mul_f32_e32 v97, v93, v161
	v_mul_f32_e32 v86, v82, v162
	v_mul_f32_e32 v87, v83, v163
	v_mul_f32_e32 v88, v84, v164
	v_mul_f32_e32 v89, v85, v0
	v_cvt_pk_bf16_f32 v90, v94, v95
	v_cvt_pk_bf16_f32 v91, v96, v97
	v_cvt_pk_bf16_f32 v92, v86, v87
	v_cvt_pk_bf16_f32 v93, v88, v89
	s_mov_b64 s[100:101], 0x2c000
	v_lshl_add_u64 v[150:151], v[148:149], 0, s[100:101]
	global_store_dwordx4 v[150:151], v[90:93], off
	v_mul_f32_e32 v156, 0xbfb8aa3b, v237
	v_mul_f32_e32 v157, v237, v237
	v_mul_f32_e32 v158, v78, v156
	v_mul_f32_e32 v159, v79, v156
	v_mul_f32_e32 v160, v80, v156
	v_mul_f32_e32 v161, v81, v156
	v_mul_f32_e32 v162, v70, v156
	v_mul_f32_e32 v163, v71, v156
	v_mul_f32_e32 v164, v72, v156
	v_mul_f32_e32 v0, v73, v156
	v_exp_f32_e32 v158, v158
	v_exp_f32_e32 v159, v159
	v_exp_f32_e32 v160, v160
	v_exp_f32_e32 v161, v161
	v_exp_f32_e32 v162, v162
	v_exp_f32_e32 v163, v163
	v_exp_f32_e32 v164, v164
	v_exp_f32_e32 v0, v0
	v_mul_f32_e32 v74, v78, v74
	v_mul_f32_e32 v75, v79, v75
	v_mul_f32_e32 v76, v80, v76
	v_mul_f32_e32 v77, v81, v77
	v_mul_f32_e32 v66, v70, v66
	v_mul_f32_e32 v67, v71, v67
	v_mul_f32_e32 v68, v72, v68
	v_mul_f32_e32 v69, v73, v69
	v_add_f32_e32 v158, 1.0, v158
	v_add_f32_e32 v159, 1.0, v159
	v_add_f32_e32 v160, 1.0, v160
	v_add_f32_e32 v161, 1.0, v161
	v_add_f32_e32 v162, 1.0, v162
	v_add_f32_e32 v163, 1.0, v163
	v_add_f32_e32 v164, 1.0, v164
	v_add_f32_e32 v0, 1.0, v0
	v_rcp_f32_e32 v158, v158
	v_rcp_f32_e32 v159, v159
	v_rcp_f32_e32 v160, v160
	v_rcp_f32_e32 v161, v161
	v_rcp_f32_e32 v162, v162
	v_rcp_f32_e32 v163, v163
	v_rcp_f32_e32 v164, v164
	v_rcp_f32_e32 v0, v0
	v_mul_f32_e32 v158, v157, v158
	v_mul_f32_e32 v159, v157, v159
	v_mul_f32_e32 v160, v157, v160
	v_mul_f32_e32 v161, v157, v161
	v_mul_f32_e32 v162, v157, v162
	v_mul_f32_e32 v163, v157, v163
	v_mul_f32_e32 v164, v157, v164
	v_mul_f32_e32 v0, v157, v0
	v_mul_f32_e32 v78, v74, v158
	v_mul_f32_e32 v79, v75, v159
	v_mul_f32_e32 v80, v76, v160
	v_mul_f32_e32 v81, v77, v161
	v_mul_f32_e32 v70, v66, v162
	v_mul_f32_e32 v71, v67, v163
	v_mul_f32_e32 v72, v68, v164
	v_mul_f32_e32 v73, v69, v0
	v_cvt_pk_bf16_f32 v74, v78, v79
	v_cvt_pk_bf16_f32 v75, v80, v81
	v_cvt_pk_bf16_f32 v76, v70, v71
	v_cvt_pk_bf16_f32 v77, v72, v73
	s_mov_b64 s[100:101], 0x42000
	v_lshl_add_u64 v[150:151], v[148:149], 0, s[100:101]
	global_store_dwordx4 v[150:151], v[74:77], off
	v_mul_f32_e32 v156, 0xbfb8aa3b, v245
	v_mul_f32_e32 v157, v245, v245
	v_mul_f32_e32 v158, v62, v156
	v_mul_f32_e32 v159, v63, v156
	v_mul_f32_e32 v160, v64, v156
	v_mul_f32_e32 v161, v65, v156
	v_mul_f32_e32 v162, v54, v156
	v_mul_f32_e32 v163, v55, v156
	v_mul_f32_e32 v164, v56, v156
	v_mul_f32_e32 v0, v57, v156
	v_exp_f32_e32 v158, v158
	v_exp_f32_e32 v159, v159
	v_exp_f32_e32 v160, v160
	v_exp_f32_e32 v161, v161
	v_exp_f32_e32 v162, v162
	v_exp_f32_e32 v163, v163
	v_exp_f32_e32 v164, v164
	v_exp_f32_e32 v0, v0
	v_mul_f32_e32 v58, v62, v58
	v_mul_f32_e32 v59, v63, v59
	v_mul_f32_e32 v60, v64, v60
	v_mul_f32_e32 v61, v65, v61
	v_mul_f32_e32 v50, v54, v50
	v_mul_f32_e32 v51, v55, v51
	v_mul_f32_e32 v52, v56, v52
	v_mul_f32_e32 v53, v57, v53
	v_add_f32_e32 v158, 1.0, v158
	v_add_f32_e32 v159, 1.0, v159
	v_add_f32_e32 v160, 1.0, v160
	v_add_f32_e32 v161, 1.0, v161
	v_add_f32_e32 v162, 1.0, v162
	v_add_f32_e32 v163, 1.0, v163
	v_add_f32_e32 v164, 1.0, v164
	v_add_f32_e32 v0, 1.0, v0
	v_rcp_f32_e32 v158, v158
	v_rcp_f32_e32 v159, v159
	v_rcp_f32_e32 v160, v160
	v_rcp_f32_e32 v161, v161
	v_rcp_f32_e32 v162, v162
	v_rcp_f32_e32 v163, v163
	v_rcp_f32_e32 v164, v164
	v_rcp_f32_e32 v0, v0
	v_mul_f32_e32 v158, v157, v158
	v_mul_f32_e32 v159, v157, v159
	v_mul_f32_e32 v160, v157, v160
	v_mul_f32_e32 v161, v157, v161
	v_mul_f32_e32 v162, v157, v162
	v_mul_f32_e32 v163, v157, v163
	v_mul_f32_e32 v164, v157, v164
	v_mul_f32_e32 v0, v157, v0
	v_mul_f32_e32 v62, v58, v158
	v_mul_f32_e32 v63, v59, v159
	v_mul_f32_e32 v64, v60, v160
	v_mul_f32_e32 v65, v61, v161
	v_mul_f32_e32 v54, v50, v162
	v_mul_f32_e32 v55, v51, v163
	v_mul_f32_e32 v56, v52, v164
	v_mul_f32_e32 v57, v53, v0
	v_cvt_pk_bf16_f32 v58, v62, v63
	v_cvt_pk_bf16_f32 v59, v64, v65
	v_cvt_pk_bf16_f32 v60, v54, v55
	v_cvt_pk_bf16_f32 v61, v56, v57
	s_mov_b64 s[100:101], 0xb0000
	v_lshl_add_u64 v[150:151], v[148:149], 0, s[100:101]
	global_store_dwordx4 v[150:151], v[58:61], off
	v_mul_f32_e32 v156, 0xbfb8aa3b, v247
	v_mul_f32_e32 v157, v247, v247
	v_mul_f32_e32 v158, v46, v156
	v_mul_f32_e32 v159, v47, v156
	v_mul_f32_e32 v160, v48, v156
	v_mul_f32_e32 v161, v49, v156
	v_mul_f32_e32 v162, v38, v156
	v_mul_f32_e32 v163, v39, v156
	v_mul_f32_e32 v164, v40, v156
	v_mul_f32_e32 v0, v41, v156
	v_exp_f32_e32 v158, v158
	v_exp_f32_e32 v159, v159
	v_exp_f32_e32 v160, v160
	v_exp_f32_e32 v161, v161
	v_exp_f32_e32 v162, v162
	v_exp_f32_e32 v163, v163
	v_exp_f32_e32 v164, v164
	v_exp_f32_e32 v0, v0
	v_mul_f32_e32 v42, v46, v42
	v_mul_f32_e32 v43, v47, v43
	v_mul_f32_e32 v44, v48, v44
	v_mul_f32_e32 v45, v49, v45
	v_mul_f32_e32 v34, v38, v34
	v_mul_f32_e32 v35, v39, v35
	v_mul_f32_e32 v36, v40, v36
; __device__ __forceinline__ unsigned cvt_pk_bf16(float lo, float hi) { unsigned r; asm volatile("v_cvt_pk_bf16_f32 %0, %1, %2" : "=v"(r) : "v"(lo), "v"(hi)); return r; }
; __device__ __forceinline__ float silu_mul(float g, float u, float c1, float c2) { const float e = __builtin_amdgcn_exp2f(g * c1); return (g * u) * (c2 * __builtin_amdgcn_rcpf(1.0f + e)); }
;     __device__ __forceinline__ void operator()(const f32x4 (&acc)[2][2][4][2], const Unit& u, int wr, int wc, int fr, int fq) const {
;     ...
;             for (int m = 0; m < 4; ++m) { bf16_t* rowp = O + (size_t)(row0 + ai * HALF + m * 16) * ldc + col0;
;                 const float rs = rsv[ai][m], c1 = rs * -1.4426950408889634f, c2 = rs * rs; const f32x4 g0 = acc[ai][0][m][0], g1 = acc[ai][0][m][1], u0 = acc[ai][1][m][0], u1 = acc[ai][1][m][1];
;                 u32x4 w; w.x = cvt_pk_bf16(silu_mul(g0[0], u0[0], c1, c2), silu_mul(g0[1], u0[1], c1, c2)); w.y = cvt_pk_bf16(silu_mul(g0[2], u0[2], c1, c2), silu_mul(g0[3], u0[3], c1, c2));
;                 w.z = cvt_pk_bf16(silu_mul(g1[0], u1[0], c1, c2), silu_mul(g1[1], u1[1], c1, c2)); w.w = cvt_pk_bf16(silu_mul(g1[2], u1[2], c1, c2), silu_mul(g1[3], u1[3], c1, c2));
;                 *(u32x4*)rowp = w; }
	v_mul_f32_e32 v37, v41, v37
	v_add_f32_e32 v158, 1.0, v158
	v_add_f32_e32 v159, 1.0, v159
	v_add_f32_e32 v160, 1.0, v160
	v_add_f32_e32 v161, 1.0, v161
	v_add_f32_e32 v162, 1.0, v162
	v_add_f32_e32 v163, 1.0, v163
	v_add_f32_e32 v164, 1.0, v164
	v_add_f32_e32 v0, 1.0, v0
	v_rcp_f32_e32 v158, v158
	v_rcp_f32_e32 v159, v159
	v_rcp_f32_e32 v160, v160
	v_rcp_f32_e32 v161, v161
	v_rcp_f32_e32 v162, v162
	v_rcp_f32_e32 v163, v163
	v_rcp_f32_e32 v164, v164
	v_rcp_f32_e32 v0, v0
	v_mul_f32_e32 v158, v157, v158
	v_mul_f32_e32 v159, v157, v159
	v_mul_f32_e32 v160, v157, v160
	v_mul_f32_e32 v161, v157, v161
	v_mul_f32_e32 v162, v157, v162
	v_mul_f32_e32 v163, v157, v163
	v_mul_f32_e32 v164, v157, v164
	v_mul_f32_e32 v0, v157, v0
	v_mul_f32_e32 v46, v42, v158
	v_mul_f32_e32 v47, v43, v159
	v_mul_f32_e32 v48, v44, v160
	v_mul_f32_e32 v49, v45, v161
	v_mul_f32_e32 v38, v34, v162
	v_mul_f32_e32 v39, v35, v163
	v_mul_f32_e32 v40, v36, v164
	v_mul_f32_e32 v41, v37, v0
	v_cvt_pk_bf16_f32 v42, v46, v47
	v_cvt_pk_bf16_f32 v43, v48, v49
	v_cvt_pk_bf16_f32 v44, v38, v39
	v_cvt_pk_bf16_f32 v45, v40, v41
	s_mov_b64 s[100:101], 0xc6000
	v_lshl_add_u64 v[150:151], v[148:149], 0, s[100:101]
	global_store_dwordx4 v[150:151], v[42:45], off
	v_mul_f32_e32 v156, 0xbfb8aa3b, v252
	v_mul_f32_e32 v157, v252, v252
	v_mul_f32_e32 v158, v30, v156
	v_mul_f32_e32 v159, v31, v156
	v_mul_f32_e32 v160, v32, v156
	v_mul_f32_e32 v161, v33, v156
	v_mul_f32_e32 v162, v22, v156
	v_mul_f32_e32 v163, v23, v156
	v_mul_f32_e32 v164, v24, v156
	v_mul_f32_e32 v0, v25, v156
	v_exp_f32_e32 v158, v158
	v_exp_f32_e32 v159, v159
	v_exp_f32_e32 v160, v160
	v_exp_f32_e32 v161, v161
	v_exp_f32_e32 v162, v162
	v_exp_f32_e32 v163, v163
	v_exp_f32_e32 v164, v164
	v_exp_f32_e32 v0, v0
	v_mul_f32_e32 v26, v30, v26
	v_mul_f32_e32 v27, v31, v27
	v_mul_f32_e32 v28, v32, v28
	v_mul_f32_e32 v29, v33, v29
	v_mul_f32_e32 v18, v22, v18
	v_mul_f32_e32 v19, v23, v19
	v_mul_f32_e32 v20, v24, v20
	v_mul_f32_e32 v21, v25, v21
	v_add_f32_e32 v158, 1.0, v158
	v_add_f32_e32 v159, 1.0, v159
	v_add_f32_e32 v160, 1.0, v160
	v_add_f32_e32 v161, 1.0, v161
	v_add_f32_e32 v162, 1.0, v162
	v_add_f32_e32 v163, 1.0, v163
	v_add_f32_e32 v164, 1.0, v164
	v_add_f32_e32 v0, 1.0, v0
	v_rcp_f32_e32 v158, v158
	v_rcp_f32_e32 v159, v159
	v_rcp_f32_e32 v160, v160
	v_rcp_f32_e32 v161, v161
	v_rcp_f32_e32 v162, v162
	v_rcp_f32_e32 v163, v163
	v_rcp_f32_e32 v164, v164
	v_rcp_f32_e32 v0, v0
	v_mul_f32_e32 v158, v157, v158
	v_mul_f32_e32 v159, v157, v159
	v_mul_f32_e32 v160, v157, v160
	v_mul_f32_e32 v161, v157, v161
	v_mul_f32_e32 v162, v157, v162
	v_mul_f32_e32 v163, v157, v163
	v_mul_f32_e32 v164, v157, v164
	v_mul_f32_e32 v0, v157, v0
	v_mul_f32_e32 v30, v26, v158
	v_mul_f32_e32 v31, v27, v159
	v_mul_f32_e32 v32, v28, v160
	v_mul_f32_e32 v33, v29, v161
	v_mul_f32_e32 v22, v18, v162
	v_mul_f32_e32 v23, v19, v163
	v_mul_f32_e32 v24, v20, v164
	v_mul_f32_e32 v25, v21, v0
	v_cvt_pk_bf16_f32 v26, v30, v31
	v_cvt_pk_bf16_f32 v27, v32, v33
	v_cvt_pk_bf16_f32 v28, v22, v23
	v_cvt_pk_bf16_f32 v29, v24, v25
	s_mov_b64 s[100:101], 0xdc000
	v_lshl_add_u64 v[150:151], v[148:149], 0, s[100:101]
	global_store_dwordx4 v[150:151], v[26:29], off
	v_mul_f32_e32 v156, 0xbfb8aa3b, v253
	v_mul_f32_e32 v157, v253, v253
	v_mul_f32_e32 v158, v14, v156
	v_mul_f32_e32 v159, v15, v156
	v_mul_f32_e32 v160, v16, v156
	v_mul_f32_e32 v161, v17, v156
	v_mul_f32_e32 v162, v6, v156
	v_mul_f32_e32 v163, v7, v156
	v_mul_f32_e32 v164, v8, v156
	v_mul_f32_e32 v0, v9, v156
	v_exp_f32_e32 v158, v158
	v_exp_f32_e32 v159, v159
	v_exp_f32_e32 v160, v160
	v_exp_f32_e32 v161, v161
	v_exp_f32_e32 v162, v162
	v_exp_f32_e32 v163, v163
	v_exp_f32_e32 v164, v164
	v_exp_f32_e32 v0, v0
	v_mul_f32_e32 v10, v14, v10
	v_mul_f32_e32 v11, v15, v11
	v_mul_f32_e32 v12, v16, v12
	v_mul_f32_e32 v13, v17, v13
	v_mul_f32_e32 v2, v6, v2
	v_mul_f32_e32 v3, v7, v3
	v_mul_f32_e32 v4, v8, v4
	v_mul_f32_e32 v5, v9, v5
	v_add_f32_e32 v158, 1.0, v158
	v_add_f32_e32 v159, 1.0, v159
	v_add_f32_e32 v160, 1.0, v160
	v_add_f32_e32 v161, 1.0, v161
	v_add_f32_e32 v162, 1.0, v162
	v_add_f32_e32 v163, 1.0, v163
	v_add_f32_e32 v164, 1.0, v164
	v_add_f32_e32 v0, 1.0, v0
	v_rcp_f32_e32 v158, v158
	v_rcp_f32_e32 v159, v159
	v_rcp_f32_e32 v160, v160
	v_rcp_f32_e32 v161, v161
	v_rcp_f32_e32 v162, v162
	v_rcp_f32_e32 v163, v163
	v_rcp_f32_e32 v164, v164
	v_rcp_f32_e32 v0, v0
	v_mul_f32_e32 v158, v157, v158
	v_mul_f32_e32 v159, v157, v159
	v_mul_f32_e32 v160, v157, v160
	v_mul_f32_e32 v161, v157, v161
	v_mul_f32_e32 v162, v157, v162
	v_mul_f32_e32 v163, v157, v163
	v_mul_f32_e32 v164, v157, v164
	v_mul_f32_e32 v0, v157, v0
	v_mul_f32_e32 v14, v10, v158
	v_mul_f32_e32 v15, v11, v159
	v_mul_f32_e32 v16, v12, v160
	v_mul_f32_e32 v17, v13, v161
	v_mul_f32_e32 v6, v2, v162
	v_mul_f32_e32 v7, v3, v163
	v_mul_f32_e32 v8, v4, v164
	v_mul_f32_e32 v9, v5, v0
	v_cvt_pk_bf16_f32 v10, v14, v15
	v_cvt_pk_bf16_f32 v11, v16, v17
	v_cvt_pk_bf16_f32 v12, v6, v7
	v_cvt_pk_bf16_f32 v13, v8, v9
	s_mov_b64 s[100:101], 0xf2000
	v_lshl_add_u64 v[150:151], v[148:149], 0, s[100:101]
	global_store_dwordx4 v[150:151], v[10:13], off
	s_mov_b64 s[30:31], -1
	s_andn2_b64 vcc, exec, s[36:37]
	s_cbranch_vccnz .LBB0_120
	s_andn2_b64 vcc, exec, s[10:11]
	s_cbranch_vccnz .LBB0_119
	s_barrier
	s_branch .LBB0_119

; template<int MODE,int THRL,bool NOMAX> __device__ __forceinline__ void attn_unit(const bf16*Qs,const bf16*__restrict__ Ks,const bf16*__restrict__ Vs,bf16*Os,int S,int q0,float sink2,float slope2,float*ssq,char*shm,int tid_in){
;   int tid_=tid_in; asm volatile("":"+v"(tid_)); const int tid=tid_,lane=tid&63,r32=lane&31,hi=lane>>5; const int wid=__builtin_amdgcn_readfirstlane(tid>>6);
;   constexpr bool LSM = NOMAX && (false);
;   int kt0=0,kend=S/KVBLK;
;   if(MODE==1){ kt0=(q0>=128?(q0-128):0)/KVBLK; const int ke=q0+QB+128; kend=(ke<S?ke:S)/KVBLK; }
;   const bf16*Qw=Qs+(long)(q0+wid*QBLK)*PITCH;
;   const bf16*Kh=Ks+(long)kt0*KVBLK*PITCH,*Vh=Vs+(long)kt0*KVBLK*PITCH;
;   const unsigned lds0=(unsigned)(uintptr_t)shm;
;   float*wsf=(float*)(shm+LDS_WS)+wid*64;
;   const bf16*ksrc=Kh+(long)lane*PITCH+wid*8;
;   const bf16*vsrc=Vh+(long)(16*(wid&3)+(lane>>2))*PITCH+(wid>>2)*32+(lane&3)*8;
;   const unsigned kdst=lds0+LDS_K+wid*1024, vdst=lds0+LDS_V+wid*1024;
;     ...
;   const int vb0=(int)(lds0+LDS_V)+((lane>>4)&1)*32+(lane&3)*8+(4*hi+((lane&15)>>2))*64;
;   const char*Kbase=shm+LDS_K; bf16x8 kf[8];
;   const lds_cptr shm3=(lds_cptr)shm; const lds_cptr kp0=shm3+LDS_K+hi*1024+r32*16; const lds_cptr vp0=shm3+LDS_V+((lane>>4)&1)*32+(lane&3)*8+(4*hi+((lane&15)>>2))*64;
;   const int NT=kend-kt0;
;   DMA_K(0,0);DMA_V(0,0);DMA_K(1,SLOTB);
;   bf16x8 qr[4];
;   #pragma unroll
;   for(int d0=0;d0<4;++d0)qr[d0]=*reinterpret_cast<const bf16x8*>(&Qw[(long)r32*PITCH+d0*16+hi*8]);
;   float mhat=0.f,l_reg=0.f;f32x16 o[2];o[0]=f32x16{};o[1]=f32x16{};f32x16 negm=f32x16{};
;   if(MODE==1){ mhat=sink2; l_reg=(hi==0)?1.f:0.f;
;     #pragma unroll
;     for(int r=0;r<16;++r)negm[r]=-sink2; }
;   if(!NOMAX)asm volatile("":"+v"(negm));
;   f32x16 lsum=f32x16{}; bf16x8 onesv;
;   #pragma unroll
;   for(int i_=0;i_<8;++i_)onesv[i_]=(short)0x3F80;
;   asm volatile("":"+v"(onesv));
;   const int qrel=wid*QBLK+r32;
;   const int qk0=q0+qrel-kt0*KVBLK-4*hi;
;     ...
;   bool resc=false;
;     ...
;   f32x16 pA0,pA1,pB0,pB1;
;   int sl_prev=0,sl_cur=0,sl_next=SLOTB,sl_n2=2*SLOTB;
;     ...
;   DMA_K(2,2*SLOTB);DMA_K(3,3*SLOTB);DMA_V(1,SLOTB);
;   WAIT_BAR(5);
;   qkt(pA0,pA1,Kbase,qr,(NOMAX?f32x16{}:negm),r32,hi);asm volatile("s_nop 15\n\ts_nop 7":"+v"(pA0),"+v"(pA1));CMASK(pA0,pA1,0);
;   START(pA0,pA1);
;   _Pragma("unroll") for(int r=0;r<16;++r)pA1[r]=__builtin_amdgcn_exp2f(pA1[r]);
;   WAIT_BAR(2);
.LBB0_549:
	s_and_b64 vcc, exec, s[4:5]
	s_cbranch_vccz .LBB0_389
	s_waitcnt lgkmcnt(0)
	v_readfirstlane_b32 s31, v251
	v_and_b32_e32 v129, 63, v251
	v_and_b32_e32 v0, 31, v251
	s_lshr_b32 s30, s31, 6
	s_and_b32 s5, s30, 3
	s_lshr_b32 s57, s30, 2
	s_lshl_b32 s4, s5, 6
	s_add_i32 s4, s4, s51
	s_lshr_b32 s40, s50, 6
	v_mul_u32_u24_e32 v214, 0xc00, v129
	s_lshl_b32 s10, s30, 4
	v_add_u32_e32 v214, s10, v214
	v_lshrrev_b32_e32 v215, 2, v129
	s_lshl_b32 s10, s5, 4
	v_add_u32_e32 v215, s10, v215
	v_mul_u32_u24_e32 v215, 0xc00, v215
	v_and_b32_e32 v217, 3, v129
	v_lshlrev_b32_e32 v217, 4, v217
	s_lshl_b32 s10, s57, 6
	v_add3_u32 v215, v215, v217, s10
	s_add_u32 s28, s28, 0x400
	s_addc_u32 s29, s29, 0
	s_add_u32 s36, s28, 0x100
	s_addc_u32 s37, s29, 0
	s_lshl_b32 s38, s30, 10
	s_add_i32 s39, s38, 0xa000
	v_lshrrev_b32_e32 v202, 5, v129
	v_lshlrev_b32_e32 v202, 10, v202
	v_lshl_add_u32 v202, v0, 4, v202
	s_lshl_b32 s10, s57, 9
	v_add_u32_e32 v202, s10, v202
	v_lshlrev_b32_e32 v217, 1, v129
	v_and_b32_e32 v217, 32, v217
	v_and_b32_e32 v126, 3, v129
	v_lshl_add_u32 v217, v126, 3, v217
	v_lshlrev_b32_e32 v126, 4, v129
	v_and_b32_e32 v126, 0xc0, v126
	v_lshrrev_b32_e32 v127, 5, v129
	v_lshl_or_b32 v126, v127, 8, v126
	s_lshl_b32 s10, s57, 11
	v_add3_u32 v217, v217, v126, s10
	s_mul_i32 s10, s4, 0xc00
	s_mul_hi_i32 s11, s4, 0xc00
	s_add_u32 s10, s52, s10
	s_addc_u32 s11, s53, s11
	s_add_u32 s14, s10, 0x18000
	s_addc_u32 s15, s11, 0
	v_mul_u32_u24_e32 v126, 0xc00, v0
	v_lshl_or_b32 v126, v127, 4, v126
	s_mov_b32 m0, s38
	s_nop 0
	global_load_lds_dwordx4 v214, s[28:29]
	s_mov_b32 m0, s39
	s_nop 0
	global_load_lds_dwordx4 v215, s[36:37]
	s_add_u32 s28, s28, 0x30000
	s_addc_u32 s29, s29, 0
	s_add_i32 m0, s38, 0x2000
	s_nop 0
	global_load_lds_dwordx4 v214, s[28:29]
	global_load_dwordx4 v[146:149], v126, s[10:11]
	global_load_dwordx4 v[150:153], v126, s[10:11] offset:32
	global_load_dwordx4 v[154:157], v126, s[10:11] offset:64
	global_load_dwordx4 v[158:161], v126, s[10:11] offset:96
	global_load_dwordx4 v[162:165], v126, s[14:15]
	global_load_dwordx4 v[166:169], v126, s[14:15] offset:32
	global_load_dwordx4 v[170:173], v126, s[14:15] offset:64
	global_load_dwordx4 v[174:177], v126, s[14:15] offset:96
	s_add_u32 s28, s28, 0x30000
	s_addc_u32 s29, s29, 0
	s_add_i32 m0, s38, 0x4000
	s_nop 0
	global_load_lds_dwordx4 v214, s[28:29]
	s_add_u32 s28, s28, 0x30000
	s_addc_u32 s29, s29, 0
	s_add_i32 m0, s38, 0x6000
	s_nop 0
	global_load_lds_dwordx4 v214, s[28:29]
	s_add_u32 s36, s36, 0x30000
	s_addc_u32 s37, s37, 0
	s_add_i32 m0, s39, 0x2000
	s_nop 0
	global_load_lds_dwordx4 v215, s[36:37]
	s_add_u32 s28, s28, 0x30000
	s_addc_u32 s29, s29, 0
	s_add_u32 s36, s36, 0x30000
	s_addc_u32 s37, s37, 0
	v_mov_b32_e32 v126, 0
	v_mov_b32_e32 v127, 0
	v_mov_b32_e32 v2, 0
	v_mov_b32_e32 v3, 0
	v_mov_b32_e32 v4, 0
	v_mov_b32_e32 v5, 0
	v_mov_b32_e32 v6, 0
	v_mov_b32_e32 v7, 0
	v_mov_b32_e32 v8, 0
	v_mov_b32_e32 v9, 0
	v_mov_b32_e32 v10, 0
	v_mov_b32_e32 v11, 0
	v_mov_b32_e32 v12, 0
	v_mov_b32_e32 v13, 0
	v_mov_b32_e32 v14, 0
	v_mov_b32_e32 v15, 0
	v_mov_b32_e32 v16, 0
	v_mov_b32_e32 v17, 0
	v_mov_b32_e32 v18, 0
	v_mov_b32_e32 v19, 0
	v_mov_b32_e32 v20, 0
	v_mov_b32_e32 v21, 0
	v_mov_b32_e32 v22, 0
	v_mov_b32_e32 v23, 0
	v_mov_b32_e32 v24, 0
	v_mov_b32_e32 v25, 0
	v_mov_b32_e32 v26, 0
	v_mov_b32_e32 v27, 0
	v_mov_b32_e32 v28, 0
	v_mov_b32_e32 v29, 0
	v_mov_b32_e32 v30, 0
	v_mov_b32_e32 v31, 0
	v_mov_b32_e32 v32, 0
	v_mov_b32_e32 v33, 0
	v_mov_b32_e32 v34, 0
	v_mov_b32_e32 v35, 0
	v_mov_b32_e32 v36, 0
	v_mov_b32_e32 v37, 0
	v_mov_b32_e32 v38, 0
	v_mov_b32_e32 v39, 0
	v_mov_b32_e32 v40, 0
	v_mov_b32_e32 v41, 0
	v_mov_b32_e32 v42, 0
	v_mov_b32_e32 v43, 0
	v_mov_b32_e32 v44, 0
	v_mov_b32_e32 v45, 0
	v_mov_b32_e32 v46, 0
	v_mov_b32_e32 v47, 0
	v_mov_b32_e32 v48, 0
	v_mov_b32_e32 v49, 0
	v_mov_b32_e32 v50, 0
	v_mov_b32_e32 v51, 0
	v_mov_b32_e32 v52, 0
	v_mov_b32_e32 v53, 0
	v_mov_b32_e32 v54, 0
	v_mov_b32_e32 v55, 0
	v_mov_b32_e32 v56, 0
	v_mov_b32_e32 v57, 0
	v_mov_b32_e32 v58, 0
	v_mov_b32_e32 v59, 0
	v_mov_b32_e32 v60, 0
	v_mov_b32_e32 v61, 0
	v_mov_b32_e32 v62, 0
	v_mov_b32_e32 v63, 0
	v_mov_b32_e32 v64, 0
	v_mov_b32_e32 v65, 0
	s_waitcnt vmcnt(0)
	s_barrier
	ds_read_b128 v[178:181], v202
	ds_read_b128 v[182:185], v202 offset:2048
	ds_read_b128 v[186:189], v202 offset:4096
	ds_read_b128 v[114:117], v202 offset:6144
	s_waitcnt lgkmcnt(0)
	v_mfma_f32_32x32x16_bf16 v[66:81], v[178:181], v[146:149], 0
	v_mfma_f32_32x32x16_bf16 v[82:97], v[178:181], v[162:165], 0
	v_mfma_f32_32x32x16_bf16 v[66:81], v[182:185], v[150:153], v[66:81]
	v_mfma_f32_32x32x16_bf16 v[82:97], v[182:185], v[166:169], v[82:97]
	v_mfma_f32_32x32x16_bf16 v[66:81], v[186:189], v[154:157], v[66:81]
	v_mfma_f32_32x32x16_bf16 v[82:97], v[186:189], v[170:173], v[82:97]
	v_mfma_f32_32x32x16_bf16 v[66:81], v[114:117], v[158:161], v[66:81]
	v_mfma_f32_32x32x16_bf16 v[82:97], v[114:117], v[174:177], v[82:97]
	s_nop 15
	s_nop 7
	v_exp_f32_e32 v66, v66
	v_exp_f32_e32 v67, v67
	v_exp_f32_e32 v68, v68
	v_exp_f32_e32 v69, v69
	v_exp_f32_e32 v70, v70
	v_exp_f32_e32 v71, v71
	v_exp_f32_e32 v72, v72
	v_exp_f32_e32 v73, v73
	v_exp_f32_e32 v74, v74
	v_exp_f32_e32 v75, v75
	v_exp_f32_e32 v76, v76
	v_exp_f32_e32 v77, v77
	v_exp_f32_e32 v78, v78
	v_exp_f32_e32 v79, v79
	v_exp_f32_e32 v80, v80
	v_exp_f32_e32 v81, v81
	v_exp_f32_e32 v82, v82
	v_exp_f32_e32 v83, v83
	v_exp_f32_e32 v84, v84
	v_exp_f32_e32 v85, v85
	v_exp_f32_e32 v86, v86
	v_exp_f32_e32 v87, v87
	v_exp_f32_e32 v88, v88
	v_exp_f32_e32 v89, v89
	v_exp_f32_e32 v90, v90
	v_exp_f32_e32 v91, v91
	v_exp_f32_e32 v92, v92
	v_exp_f32_e32 v93, v93
	v_exp_f32_e32 v94, v94
	v_exp_f32_e32 v95, v95
	v_exp_f32_e32 v96, v96
	v_exp_f32_e32 v97, v97
	s_waitcnt vmcnt(0) lgkmcnt(0)
	s_barrier
	s_add_i32 m0, s38, 0x8000
	s_nop 0
	global_load_lds_dwordx4 v214, s[28:29]
	s_add_i32 m0, s39, 0x4000
	s_nop 0
	global_load_lds_dwordx4 v215, s[36:37]
	s_add_u32 s28, s28, 0x30000
	s_addc_u32 s29, s29, 0
	s_add_u32 s36, s36, 0x30000
	s_addc_u32 s37, s37, 0
	s_mov_b32 s15, 0
	s_movk_i32 s14, 0x2000
	s_movk_i32 s44, 0x4000
	s_movk_i32 s51, 0x6000
	v_add_u32_e32 v129, s14, v202
	ds_read_b128 v[178:181], v129
	ds_read_b128 v[182:185], v129 offset:2048
	ds_read_b128 v[186:189], v129 offset:4096
	ds_read_b128 v[114:117], v129 offset:6144
	s_mov_b32 s18, 1
; #define WAIT_BAR(N) asm volatile("s_waitcnt vmcnt(" #N ") lgkmcnt(0)\n\ts_barrier":::"memory")
;   #define RESC() do{ if(resc){ asm volatile("s_waitcnt lgkmcnt(0)":::"memory"); \
;       _Pragma("unroll") for(int d_=0;d_<2;++d_) _Pragma("unroll") for(int r=0;r<16;++r)o[d_][r]*=wsf[crow(r,hi)]; } }while(0)
;   #define ROT() do{sl_prev=sl_cur;sl_cur=sl_next;sl_next=sl_n2;sl_n2=(sl_n2==(NSLOT-1)*SLOTB)?0:sl_n2+SLOTB;}while(0)
; template<int MODE,int THRL,bool NOMAX> __device__ __forceinline__ void attn_unit(const bf16*Qs,const bf16*__restrict__ Ks,const bf16*__restrict__ Vs,bf16*Os,int S,int q0,float sink2,float slope2,float*ssq,char*shm,int tid_in){
;     ...
;   int t=1;
;   for(;t+5<NT;t+=2){
;     STEP(pB0,pB1,pA0,pA1,t,true,true,true);     WAIT_BAR(2); RESC(); ROT();
;     STEP(pA0,pA1,pB0,pB1,t+1,true,true,true);   RESC(); ROT();
;   }
.Lkvs_loop:
	v_add_u32_e32 v129, s15, v217
	ds_read_b64_tr_b16 v[210:211], v129 offset:40960
	s_waitcnt lgkmcnt(4)
	v_mfma_f32_32x32x16_bf16 v[98:113], v[178:181], v[146:149], 0
	v_add_f32_e32 v0, v66, v67
	v_add_f32_e32 v0, v68, v0
	v_add_f32_e32 v0, v69, v0
	v_cvt_pk_bf16_f32 v190, v66, v67
	v_cvt_pk_bf16_f32 v191, v68, v69
	ds_read_b64_tr_b16 v[212:213], v129 offset:41472
	v_mfma_f32_32x32x16_bf16 v[130:145], v[178:181], v[162:165], 0
	v_add_f32_e32 v0, v70, v0
	v_add_f32_e32 v0, v71, v0
	v_add_f32_e32 v0, v72, v0
	v_add_f32_e32 v0, v73, v0
	v_cvt_pk_bf16_f32 v192, v70, v71
	v_cvt_pk_bf16_f32 v193, v72, v73
	ds_read_b64_tr_b16 v[118:119], v129 offset:45056
	s_waitcnt lgkmcnt(5)
	v_mfma_f32_32x32x16_bf16 v[98:113], v[182:185], v[150:153], v[98:113]
	v_add_f32_e32 v0, v74, v0
	v_add_f32_e32 v0, v75, v0
	v_add_f32_e32 v0, v76, v0
	v_add_f32_e32 v0, v77, v0
	v_cvt_pk_bf16_f32 v194, v74, v75
	v_cvt_pk_bf16_f32 v195, v76, v77
	ds_read_b64_tr_b16 v[120:121], v129 offset:45568
	v_mfma_f32_32x32x16_bf16 v[130:145], v[182:185], v[166:169], v[130:145]
	v_add_f32_e32 v0, v78, v0
	v_add_f32_e32 v0, v79, v0
	v_add_f32_e32 v0, v80, v0
	v_add_f32_e32 v0, v81, v0
	v_add_f32_e32 v126, v126, v0
	v_cvt_pk_bf16_f32 v196, v78, v79
	v_cvt_pk_bf16_f32 v197, v80, v81
	ds_read_b64_tr_b16 v[122:123], v129 offset:41984
	s_waitcnt lgkmcnt(6)
	v_mfma_f32_32x32x16_bf16 v[98:113], v[186:189], v[154:157], v[98:113]
	v_add_f32_e32 v0, v82, v83
	v_add_f32_e32 v0, v84, v0
	v_add_f32_e32 v0, v85, v0
	v_cvt_pk_bf16_f32 v198, v82, v83
	v_cvt_pk_bf16_f32 v199, v84, v85
	ds_read_b64_tr_b16 v[124:125], v129 offset:42496
	v_mfma_f32_32x32x16_bf16 v[130:145], v[186:189], v[170:173], v[130:145]
	v_add_f32_e32 v0, v86, v0
	v_add_f32_e32 v0, v87, v0
	v_add_f32_e32 v0, v88, v0
	v_add_f32_e32 v0, v89, v0
	v_cvt_pk_bf16_f32 v200, v86, v87
	v_cvt_pk_bf16_f32 v201, v88, v89
	ds_read_b64_tr_b16 v[218:219], v129 offset:46080
	s_waitcnt lgkmcnt(7)
	v_mfma_f32_32x32x16_bf16 v[98:113], v[114:117], v[158:161], v[98:113]
	v_add_f32_e32 v0, v90, v0
	v_add_f32_e32 v0, v91, v0
	v_add_f32_e32 v0, v92, v0
	v_add_f32_e32 v0, v93, v0
	v_cvt_pk_bf16_f32 v206, v90, v91
	v_cvt_pk_bf16_f32 v207, v92, v93
	ds_read_b64_tr_b16 v[220:221], v129 offset:46592
	v_mfma_f32_32x32x16_bf16 v[130:145], v[114:117], v[174:177], v[130:145]
	v_add_f32_e32 v0, v94, v0
	v_add_f32_e32 v0, v95, v0
	v_add_f32_e32 v0, v96, v0
	v_add_f32_e32 v0, v97, v0
	v_add_f32_e32 v127, v127, v0
	v_cvt_pk_bf16_f32 v208, v94, v95
	v_cvt_pk_bf16_f32 v209, v96, v97
	s_add_i32 s10, s15, s38
	s_mov_b32 m0, s10
	s_add_i32 s10, s51, s39
	global_load_lds_dwordx4 v214, s[28:29]
	s_mov_b32 m0, s10
	s_add_u32 s28, s28, 0x30000
	global_load_lds_dwordx4 v215, s[36:37]
	s_addc_u32 s29, s29, 0
	s_add_u32 s36, s36, 0x30000
	s_addc_u32 s37, s37, 0
	v_add_u32_e32 v129, s44, v202
	s_waitcnt lgkmcnt(6)
	v_mfma_f32_32x32x16_bf16 v[2:17], v[190:193], v[210:213], v[2:17]
	v_exp_f32_e32 v98, v98
	v_exp_f32_e32 v99, v99
	v_exp_f32_e32 v100, v100
	v_exp_f32_e32 v101, v101
	s_waitcnt lgkmcnt(4)
	v_mfma_f32_32x32x16_bf16 v[18:33], v[190:193], v[118:121], v[18:33]
	v_exp_f32_e32 v102, v102
	v_exp_f32_e32 v103, v103
	v_exp_f32_e32 v104, v104
	v_exp_f32_e32 v105, v105
	ds_read_b128 v[178:181], v129
	v_mfma_f32_32x32x16_bf16 v[34:49], v[198:201], v[210:213], v[34:49]
	v_exp_f32_e32 v106, v106
	v_exp_f32_e32 v107, v107
	v_exp_f32_e32 v108, v108
	v_exp_f32_e32 v109, v109
	ds_read_b128 v[182:185], v129 offset:2048
	v_mfma_f32_32x32x16_bf16 v[50:65], v[198:201], v[118:121], v[50:65]
	v_exp_f32_e32 v110, v110
	v_exp_f32_e32 v111, v111
	v_exp_f32_e32 v112, v112
	v_exp_f32_e32 v113, v113
	ds_read_b128 v[186:189], v129 offset:4096
	s_waitcnt lgkmcnt(5)
	v_mfma_f32_32x32x16_bf16 v[2:17], v[194:197], v[122:125], v[2:17]
	v_exp_f32_e32 v130, v130
	v_exp_f32_e32 v131, v131
	v_exp_f32_e32 v132, v132
	v_exp_f32_e32 v133, v133
	ds_read_b128 v[114:117], v129 offset:6144
	s_waitcnt lgkmcnt(4)
	v_mfma_f32_32x32x16_bf16 v[18:33], v[194:197], v[218:221], v[18:33]
	v_exp_f32_e32 v134, v134
	v_exp_f32_e32 v135, v135
	v_exp_f32_e32 v136, v136
	v_exp_f32_e32 v137, v137
	v_mfma_f32_32x32x16_bf16 v[34:49], v[206:209], v[122:125], v[34:49]
	v_exp_f32_e32 v138, v138
	v_exp_f32_e32 v139, v139
	v_exp_f32_e32 v140, v140
	v_exp_f32_e32 v141, v141
	v_mfma_f32_32x32x16_bf16 v[50:65], v[206:209], v[218:221], v[50:65]
	v_exp_f32_e32 v142, v142
	v_exp_f32_e32 v143, v143
	v_exp_f32_e32 v144, v144
	v_exp_f32_e32 v145, v145
	s_mov_b32 s15, s14
	s_mov_b32 s14, s44
	s_mov_b32 s44, s51
	s_add_i32 s10, s51, 0x2000
	s_cmpk_lg_u32 s51, 0x8000
	s_cselect_b32 s51, s10, 0
	s_waitcnt vmcnt(2) lgkmcnt(0)
	s_barrier
; #define WAIT_BAR(N) asm volatile("s_waitcnt vmcnt(" #N ") lgkmcnt(0)\n\ts_barrier":::"memory")
;   #define RESC() do{ if(resc){ asm volatile("s_waitcnt lgkmcnt(0)":::"memory"); \
;       _Pragma("unroll") for(int d_=0;d_<2;++d_) _Pragma("unroll") for(int r=0;r<16;++r)o[d_][r]*=wsf[crow(r,hi)]; } }while(0)
;   #define ROT() do{sl_prev=sl_cur;sl_cur=sl_next;sl_next=sl_n2;sl_n2=(sl_n2==(NSLOT-1)*SLOTB)?0:sl_n2+SLOTB;}while(0)
; template<int MODE,int THRL,bool NOMAX> __device__ __forceinline__ void attn_unit(const bf16*Qs,const bf16*__restrict__ Ks,const bf16*__restrict__ Vs,bf16*Os,int S,int q0,float sink2,float slope2,float*ssq,char*shm,int tid_in){
;     ...
;   int t=1;
;   for(;t+5<NT;t+=2){
;     STEP(pB0,pB1,pA0,pA1,t,true,true,true);     WAIT_BAR(2); RESC(); ROT();
;     STEP(pA0,pA1,pB0,pB1,t+1,true,true,true);   RESC(); ROT();
;   }
	v_add_u32_e32 v129, s15, v217
	ds_read_b64_tr_b16 v[210:211], v129 offset:40960
	s_waitcnt lgkmcnt(4)
	v_mfma_f32_32x32x16_bf16 v[66:81], v[178:181], v[146:149], 0
	v_add_f32_e32 v0, v98, v99
	v_add_f32_e32 v0, v100, v0
	v_add_f32_e32 v0, v101, v0
	v_cvt_pk_bf16_f32 v190, v98, v99
	v_cvt_pk_bf16_f32 v191, v100, v101
	ds_read_b64_tr_b16 v[212:213], v129 offset:41472
	v_mfma_f32_32x32x16_bf16 v[82:97], v[178:181], v[162:165], 0
	v_add_f32_e32 v0, v102, v0
	v_add_f32_e32 v0, v103, v0
	v_add_f32_e32 v0, v104, v0
	v_add_f32_e32 v0, v105, v0
	v_cvt_pk_bf16_f32 v192, v102, v103
	v_cvt_pk_bf16_f32 v193, v104, v105
	ds_read_b64_tr_b16 v[118:119], v129 offset:45056
	s_waitcnt lgkmcnt(5)
	v_mfma_f32_32x32x16_bf16 v[66:81], v[182:185], v[150:153], v[66:81]
	v_add_f32_e32 v0, v106, v0
	v_add_f32_e32 v0, v107, v0
	v_add_f32_e32 v0, v108, v0
	v_add_f32_e32 v0, v109, v0
	v_cvt_pk_bf16_f32 v194, v106, v107
	v_cvt_pk_bf16_f32 v195, v108, v109
	ds_read_b64_tr_b16 v[120:121], v129 offset:45568
	v_mfma_f32_32x32x16_bf16 v[82:97], v[182:185], v[166:169], v[82:97]
	v_add_f32_e32 v0, v110, v0
	v_add_f32_e32 v0, v111, v0
	v_add_f32_e32 v0, v112, v0
	v_add_f32_e32 v0, v113, v0
	v_add_f32_e32 v126, v126, v0
	v_cvt_pk_bf16_f32 v196, v110, v111
	v_cvt_pk_bf16_f32 v197, v112, v113
	ds_read_b64_tr_b16 v[122:123], v129 offset:41984
	s_waitcnt lgkmcnt(6)
	v_mfma_f32_32x32x16_bf16 v[66:81], v[186:189], v[154:157], v[66:81]
	v_add_f32_e32 v0, v130, v131
	v_add_f32_e32 v0, v132, v0
	v_add_f32_e32 v0, v133, v0
	v_cvt_pk_bf16_f32 v198, v130, v131
	v_cvt_pk_bf16_f32 v199, v132, v133
	ds_read_b64_tr_b16 v[124:125], v129 offset:42496
	v_mfma_f32_32x32x16_bf16 v[82:97], v[186:189], v[170:173], v[82:97]
	v_add_f32_e32 v0, v134, v0
	v_add_f32_e32 v0, v135, v0
	v_add_f32_e32 v0, v136, v0
	v_add_f32_e32 v0, v137, v0
	v_cvt_pk_bf16_f32 v200, v134, v135
	v_cvt_pk_bf16_f32 v201, v136, v137
	ds_read_b64_tr_b16 v[218:219], v129 offset:46080
	s_waitcnt lgkmcnt(7)
	v_mfma_f32_32x32x16_bf16 v[66:81], v[114:117], v[158:161], v[66:81]
	v_add_f32_e32 v0, v138, v0
	v_add_f32_e32 v0, v139, v0
	v_add_f32_e32 v0, v140, v0
	v_add_f32_e32 v0, v141, v0
	v_cvt_pk_bf16_f32 v206, v138, v139
	v_cvt_pk_bf16_f32 v207, v140, v141
	ds_read_b64_tr_b16 v[220:221], v129 offset:46592
	v_mfma_f32_32x32x16_bf16 v[82:97], v[114:117], v[174:177], v[82:97]
	v_add_f32_e32 v0, v142, v0
	v_add_f32_e32 v0, v143, v0
	v_add_f32_e32 v0, v144, v0
	v_add_f32_e32 v0, v145, v0
	v_add_f32_e32 v127, v127, v0
	v_cvt_pk_bf16_f32 v208, v142, v143
	v_cvt_pk_bf16_f32 v209, v144, v145
	s_add_i32 s10, s15, s38
	s_mov_b32 m0, s10
	s_add_i32 s10, s51, s39
	global_load_lds_dwordx4 v214, s[28:29]
	s_mov_b32 m0, s10
	s_add_u32 s28, s28, 0x30000
	global_load_lds_dwordx4 v215, s[36:37]
	s_addc_u32 s29, s29, 0
	s_add_u32 s36, s36, 0x30000
	s_addc_u32 s37, s37, 0
	v_add_u32_e32 v129, s44, v202
	s_waitcnt lgkmcnt(6)
	v_mfma_f32_32x32x16_bf16 v[2:17], v[190:193], v[210:213], v[2:17]
	v_exp_f32_e32 v66, v66
	v_exp_f32_e32 v67, v67
	v_exp_f32_e32 v68, v68
	v_exp_f32_e32 v69, v69
	s_waitcnt lgkmcnt(4)
	v_mfma_f32_32x32x16_bf16 v[18:33], v[190:193], v[118:121], v[18:33]
	v_exp_f32_e32 v70, v70
	v_exp_f32_e32 v71, v71
	v_exp_f32_e32 v72, v72
	v_exp_f32_e32 v73, v73
	ds_read_b128 v[178:181], v129
	v_mfma_f32_32x32x16_bf16 v[34:49], v[198:201], v[210:213], v[34:49]
	v_exp_f32_e32 v74, v74
	v_exp_f32_e32 v75, v75
	v_exp_f32_e32 v76, v76
	v_exp_f32_e32 v77, v77
	ds_read_b128 v[182:185], v129 offset:2048
	v_mfma_f32_32x32x16_bf16 v[50:65], v[198:201], v[118:121], v[50:65]
	v_exp_f32_e32 v78, v78
	v_exp_f32_e32 v79, v79
	v_exp_f32_e32 v80, v80
	v_exp_f32_e32 v81, v81
	ds_read_b128 v[186:189], v129 offset:4096
	s_waitcnt lgkmcnt(5)
	v_mfma_f32_32x32x16_bf16 v[2:17], v[194:197], v[122:125], v[2:17]
	v_exp_f32_e32 v82, v82
	v_exp_f32_e32 v83, v83
	v_exp_f32_e32 v84, v84
	v_exp_f32_e32 v85, v85
	ds_read_b128 v[114:117], v129 offset:6144
	s_waitcnt lgkmcnt(4)
	v_mfma_f32_32x32x16_bf16 v[18:33], v[194:197], v[218:221], v[18:33]
	v_exp_f32_e32 v86, v86
	v_exp_f32_e32 v87, v87
	v_exp_f32_e32 v88, v88
	v_exp_f32_e32 v89, v89
	v_mfma_f32_32x32x16_bf16 v[34:49], v[206:209], v[122:125], v[34:49]
	v_exp_f32_e32 v90, v90
	v_exp_f32_e32 v91, v91
	v_exp_f32_e32 v92, v92
	v_exp_f32_e32 v93, v93
	v_mfma_f32_32x32x16_bf16 v[50:65], v[206:209], v[218:221], v[50:65]
	v_exp_f32_e32 v94, v94
	v_exp_f32_e32 v95, v95
	v_exp_f32_e32 v96, v96
	v_exp_f32_e32 v97, v97
	s_mov_b32 s15, s14
	s_mov_b32 s14, s44
	s_mov_b32 s44, s51
	s_add_i32 s10, s51, 0x2000
	s_cmpk_lg_u32 s51, 0x8000
	s_cselect_b32 s51, s10, 0
	s_add_i32 s18, s18, 2
	s_add_i32 s10, s18, 1
	s_cmp_lt_u32 s10, s40
	s_cbranch_scc1 .Lkvs_loop
;   #define RESC() do{ if(resc){ asm volatile("s_waitcnt lgkmcnt(0)":::"memory"); \
;       _Pragma("unroll") for(int d_=0;d_<2;++d_) _Pragma("unroll") for(int r=0;r<16;++r)o[d_][r]*=wsf[crow(r,hi)]; } }while(0)
; template<int MODE,int THRL,bool NOMAX> __device__ __forceinline__ void attn_unit(const bf16*Qs,const bf16*__restrict__ Ks,const bf16*__restrict__ Vs,bf16*Os,int S,int q0,float sink2,float slope2,float*ssq,char*shm,int tid_in){
;     ...
;   STEP(pB0,pB1,pA0,pA1,NT-1,false,false,false); RESC();
	v_add_u32_e32 v129, s15, v217
	ds_read_b64_tr_b16 v[210:211], v129 offset:40960
	s_waitcnt lgkmcnt(4)
	v_mfma_f32_32x32x16_bf16 v[98:113], v[178:181], v[146:149], 0
	v_add_f32_e32 v0, v66, v67
	v_add_f32_e32 v0, v68, v0
	v_add_f32_e32 v0, v69, v0
	v_cvt_pk_bf16_f32 v190, v66, v67
	v_cvt_pk_bf16_f32 v191, v68, v69
	ds_read_b64_tr_b16 v[212:213], v129 offset:41472
	v_mfma_f32_32x32x16_bf16 v[130:145], v[178:181], v[162:165], 0
	v_add_f32_e32 v0, v70, v0
	v_add_f32_e32 v0, v71, v0
	v_add_f32_e32 v0, v72, v0
	v_add_f32_e32 v0, v73, v0
	v_cvt_pk_bf16_f32 v192, v70, v71
	v_cvt_pk_bf16_f32 v193, v72, v73
	ds_read_b64_tr_b16 v[118:119], v129 offset:45056
	s_waitcnt lgkmcnt(5)
	v_mfma_f32_32x32x16_bf16 v[98:113], v[182:185], v[150:153], v[98:113]
	v_add_f32_e32 v0, v74, v0
	v_add_f32_e32 v0, v75, v0
	v_add_f32_e32 v0, v76, v0
	v_add_f32_e32 v0, v77, v0
	v_cvt_pk_bf16_f32 v194, v74, v75
	v_cvt_pk_bf16_f32 v195, v76, v77
	ds_read_b64_tr_b16 v[120:121], v129 offset:45568
	v_mfma_f32_32x32x16_bf16 v[130:145], v[182:185], v[166:169], v[130:145]
	v_add_f32_e32 v0, v78, v0
	v_add_f32_e32 v0, v79, v0
	v_add_f32_e32 v0, v80, v0
	v_add_f32_e32 v0, v81, v0
	v_add_f32_e32 v126, v126, v0
	v_cvt_pk_bf16_f32 v196, v78, v79
	v_cvt_pk_bf16_f32 v197, v80, v81
	ds_read_b64_tr_b16 v[122:123], v129 offset:41984
	s_waitcnt lgkmcnt(6)
	v_mfma_f32_32x32x16_bf16 v[98:113], v[186:189], v[154:157], v[98:113]
	v_add_f32_e32 v0, v82, v83
	v_add_f32_e32 v0, v84, v0
	v_add_f32_e32 v0, v85, v0
	v_cvt_pk_bf16_f32 v198, v82, v83
	v_cvt_pk_bf16_f32 v199, v84, v85
	ds_read_b64_tr_b16 v[124:125], v129 offset:42496
	v_mfma_f32_32x32x16_bf16 v[130:145], v[186:189], v[170:173], v[130:145]
	v_add_f32_e32 v0, v86, v0
	v_add_f32_e32 v0, v87, v0
	v_add_f32_e32 v0, v88, v0
	v_add_f32_e32 v0, v89, v0
	v_cvt_pk_bf16_f32 v200, v86, v87
	v_cvt_pk_bf16_f32 v201, v88, v89
	ds_read_b64_tr_b16 v[218:219], v129 offset:46080
	s_waitcnt lgkmcnt(7)
	v_mfma_f32_32x32x16_bf16 v[98:113], v[114:117], v[158:161], v[98:113]
	v_add_f32_e32 v0, v90, v0
	v_add_f32_e32 v0, v91, v0
	v_add_f32_e32 v0, v92, v0
	v_add_f32_e32 v0, v93, v0
	v_cvt_pk_bf16_f32 v206, v90, v91
	v_cvt_pk_bf16_f32 v207, v92, v93
	ds_read_b64_tr_b16 v[220:221], v129 offset:46592
	v_mfma_f32_32x32x16_bf16 v[130:145], v[114:117], v[174:177], v[130:145]
	v_add_f32_e32 v0, v94, v0
	v_add_f32_e32 v0, v95, v0
	v_add_f32_e32 v0, v96, v0
	v_add_f32_e32 v0, v97, v0
	v_add_f32_e32 v127, v127, v0
	v_cvt_pk_bf16_f32 v208, v94, v95
	v_cvt_pk_bf16_f32 v209, v96, v97
	s_add_i32 s10, s15, s38
	s_mov_b32 m0, s10
	s_add_i32 s10, s51, s39
	global_load_lds_dwordx4 v214, s[28:29]
	s_mov_b32 m0, s10
	s_add_u32 s28, s28, 0x30000
	global_load_lds_dwordx4 v215, s[36:37]
	s_addc_u32 s29, s29, 0
	s_add_u32 s36, s36, 0x30000
	s_addc_u32 s37, s37, 0
	v_add_u32_e32 v129, s44, v202
	s_waitcnt lgkmcnt(6)
	v_mfma_f32_32x32x16_bf16 v[2:17], v[190:193], v[210:213], v[2:17]
	v_exp_f32_e32 v98, v98
	v_exp_f32_e32 v99, v99
	v_exp_f32_e32 v100, v100
	v_exp_f32_e32 v101, v101
	s_waitcnt lgkmcnt(4)
	v_mfma_f32_32x32x16_bf16 v[18:33], v[190:193], v[118:121], v[18:33]
	v_exp_f32_e32 v102, v102
	v_exp_f32_e32 v103, v103
	v_exp_f32_e32 v104, v104
	v_exp_f32_e32 v105, v105
	ds_read_b128 v[178:181], v129
	v_mfma_f32_32x32x16_bf16 v[34:49], v[198:201], v[210:213], v[34:49]
	v_exp_f32_e32 v106, v106
	v_exp_f32_e32 v107, v107
	v_exp_f32_e32 v108, v108
	v_exp_f32_e32 v109, v109
	ds_read_b128 v[182:185], v129 offset:2048
	v_mfma_f32_32x32x16_bf16 v[50:65], v[198:201], v[118:121], v[50:65]
	v_exp_f32_e32 v110, v110
	v_exp_f32_e32 v111, v111
	v_exp_f32_e32 v112, v112
	v_exp_f32_e32 v113, v113
	ds_read_b128 v[186:189], v129 offset:4096
	s_waitcnt lgkmcnt(5)
	v_mfma_f32_32x32x16_bf16 v[2:17], v[194:197], v[122:125], v[2:17]
	v_exp_f32_e32 v130, v130
	v_exp_f32_e32 v131, v131
	v_exp_f32_e32 v132, v132
	v_exp_f32_e32 v133, v133
	ds_read_b128 v[114:117], v129 offset:6144
	s_waitcnt lgkmcnt(4)
	v_mfma_f32_32x32x16_bf16 v[18:33], v[194:197], v[218:221], v[18:33]
	v_exp_f32_e32 v134, v134
	v_exp_f32_e32 v135, v135
	v_exp_f32_e32 v136, v136
	v_exp_f32_e32 v137, v137
	v_mfma_f32_32x32x16_bf16 v[34:49], v[206:209], v[122:125], v[34:49]
	v_exp_f32_e32 v138, v138
	v_exp_f32_e32 v139, v139
	v_exp_f32_e32 v140, v140
	v_exp_f32_e32 v141, v141
	v_mfma_f32_32x32x16_bf16 v[50:65], v[206:209], v[218:221], v[50:65]
	v_exp_f32_e32 v142, v142
	v_exp_f32_e32 v143, v143
	v_exp_f32_e32 v144, v144
	v_exp_f32_e32 v145, v145
	s_mov_b32 s15, s14
	s_mov_b32 s14, s44
	s_mov_b32 s44, s51
	s_add_i32 s10, s51, 0x2000
	s_cmpk_lg_u32 s51, 0x8000
	s_cselect_b32 s51, s10, 0
	s_waitcnt vmcnt(2) lgkmcnt(0)
	s_barrier
; #define SBAR() __builtin_amdgcn_sched_barrier(0)
;   #define PKW(P,B) cvtpk_s(P[B],P[B+1])
;   #define LSUM(k) do{ if(LSM){ lsum=__builtin_amdgcn_mfma_f32_32x32x16_bf16(PAF(k),onesv,lsum,0,0,0); SBAR(); } }while(0)
; template<int MODE,int THRL,bool NOMAX> __device__ __forceinline__ void attn_unit(const bf16*Qs,const bf16*__restrict__ Ks,const bf16*__restrict__ Vs,bf16*Os,int S,int q0,float sink2,float slope2,float*ssq,char*shm,int tid_in){
;     ...
;   { float sacc=pB0[0]+pB0[1]; _Pragma("unroll") for(int r=2;r<16;++r)sacc+=pB0[r]; _Pragma("unroll") for(int r=0;r<16;++r)sacc+=pB1[r]; l_reg+=sacc;
;     pw0=(u32x4){PKW(pB0,0),PKW(pB0,2),PKW(pB0,4),PKW(pB0,6)};pw1=(u32x4){PKW(pB0,8),PKW(pB0,10),PKW(pB0,12),PKW(pB0,14)};pw2=(u32x4){PKW(pB1,0),PKW(pB1,2),PKW(pB1,4),PKW(pB1,6)};pw3=(u32x4){PKW(pB1,8),PKW(pB1,10),PKW(pB1,12),PKW(pB1,14)};
;     SBAR(); pv(o,vb0+sl_cur,PAF(0),PAF(1),PAF(2),PAF(3)); LSUM(0); LSUM(1); LSUM(2); LSUM(3); }
	v_add_u32_e32 v129, s15, v217
	ds_read_b64_tr_b16 v[210:211], v129 offset:40960
	ds_read_b64_tr_b16 v[212:213], v129 offset:41472
	ds_read_b64_tr_b16 v[118:119], v129 offset:45056
	ds_read_b64_tr_b16 v[120:121], v129 offset:45568
	ds_read_b64_tr_b16 v[122:123], v129 offset:41984
	ds_read_b64_tr_b16 v[124:125], v129 offset:42496
	ds_read_b64_tr_b16 v[218:219], v129 offset:46080
	ds_read_b64_tr_b16 v[220:221], v129 offset:46592
	v_add_f32_e32 v0, v98, v99
	v_add_f32_e32 v0, v100, v0
	v_add_f32_e32 v0, v101, v0
	v_add_f32_e32 v0, v102, v0
	v_add_f32_e32 v0, v103, v0
	v_add_f32_e32 v0, v104, v0
	v_add_f32_e32 v0, v105, v0
	v_add_f32_e32 v0, v106, v0
	v_add_f32_e32 v0, v107, v0
	v_add_f32_e32 v0, v108, v0
	v_add_f32_e32 v0, v109, v0
	v_add_f32_e32 v0, v110, v0
	v_add_f32_e32 v0, v111, v0
	v_add_f32_e32 v0, v112, v0
	v_add_f32_e32 v0, v113, v0
	v_add_f32_e32 v126, v126, v0
	v_cvt_pk_bf16_f32 v190, v98, v99
	v_cvt_pk_bf16_f32 v191, v100, v101
	v_cvt_pk_bf16_f32 v192, v102, v103
	v_cvt_pk_bf16_f32 v193, v104, v105
	v_cvt_pk_bf16_f32 v194, v106, v107
	v_cvt_pk_bf16_f32 v195, v108, v109
	v_cvt_pk_bf16_f32 v196, v110, v111
	v_cvt_pk_bf16_f32 v197, v112, v113
	v_add_f32_e32 v0, v130, v131
	v_add_f32_e32 v0, v132, v0
	v_add_f32_e32 v0, v133, v0
	v_add_f32_e32 v0, v134, v0
	v_add_f32_e32 v0, v135, v0
	v_add_f32_e32 v0, v136, v0
	v_add_f32_e32 v0, v137, v0
	v_add_f32_e32 v0, v138, v0
	v_add_f32_e32 v0, v139, v0
	v_add_f32_e32 v0, v140, v0
	v_add_f32_e32 v0, v141, v0
	v_add_f32_e32 v0, v142, v0
	v_add_f32_e32 v0, v143, v0
	v_add_f32_e32 v0, v144, v0
	v_add_f32_e32 v0, v145, v0
	v_add_f32_e32 v127, v127, v0
	v_cvt_pk_bf16_f32 v198, v130, v131
	v_cvt_pk_bf16_f32 v199, v132, v133
	v_cvt_pk_bf16_f32 v200, v134, v135
	v_cvt_pk_bf16_f32 v201, v136, v137
	v_cvt_pk_bf16_f32 v206, v138, v139
	v_cvt_pk_bf16_f32 v207, v140, v141
	v_cvt_pk_bf16_f32 v208, v142, v143
	v_cvt_pk_bf16_f32 v209, v144, v145
	s_nop 1
	s_waitcnt lgkmcnt(6)
	v_mfma_f32_32x32x16_bf16 v[2:17], v[190:193], v[210:213], v[2:17]
	s_waitcnt lgkmcnt(4)
	v_mfma_f32_32x32x16_bf16 v[18:33], v[190:193], v[118:121], v[18:33]
	v_mfma_f32_32x32x16_bf16 v[34:49], v[198:201], v[210:213], v[34:49]
	v_mfma_f32_32x32x16_bf16 v[50:65], v[198:201], v[118:121], v[50:65]
	s_waitcnt lgkmcnt(2)
	v_mfma_f32_32x32x16_bf16 v[2:17], v[194:197], v[122:125], v[2:17]
	s_waitcnt lgkmcnt(0)
	v_mfma_f32_32x32x16_bf16 v[18:33], v[194:197], v[218:221], v[18:33]
	v_mfma_f32_32x32x16_bf16 v[34:49], v[206:209], v[122:125], v[34:49]
	v_mfma_f32_32x32x16_bf16 v[50:65], v[206:209], v[218:221], v[50:65]
	s_waitcnt vmcnt(0) lgkmcnt(0)
	s_barrier
	v_and_b32_e32 v129, 63, v251
	v_lshlrev_b32_e32 v129, 2, v129
	s_xor_b32 s10, s30, 4
	s_lshl_b32 s11, s10, 13
	v_add_u32_e32 v186, s11, v129
	s_lshl_b32 s11, s10, 8
	s_add_i32 s11, s11, 0x10000
	v_add_u32_e32 v187, s11, v129
	s_lshl_b32 s11, s30, 13
	v_add_u32_e32 v114, s11, v129
	s_lshl_b32 s11, s30, 8
	s_add_i32 s11, s11, 0x10000
	v_add_u32_e32 v115, s11, v129
	s_cmp_eq_u32 s57, 0
	s_cbranch_scc1 .Lkvs_fin0
	ds_write_b32 v186, v2 offset:0
	ds_write_b32 v186, v3 offset:256
	ds_write_b32 v186, v4 offset:512
	ds_write_b32 v186, v5 offset:768
	ds_write_b32 v186, v6 offset:1024
	ds_write_b32 v186, v7 offset:1280
	ds_write_b32 v186, v8 offset:1536
	ds_write_b32 v186, v9 offset:1792
	ds_write_b32 v186, v10 offset:2048
	ds_write_b32 v186, v11 offset:2304
	ds_write_b32 v186, v12 offset:2560
	ds_write_b32 v186, v13 offset:2816
	ds_write_b32 v186, v14 offset:3072
	ds_write_b32 v186, v15 offset:3328
	ds_write_b32 v186, v16 offset:3584
	ds_write_b32 v186, v17 offset:3840
	ds_write_b32 v186, v18 offset:4096
	ds_write_b32 v186, v19 offset:4352
	ds_write_b32 v186, v20 offset:4608
	ds_write_b32 v186, v21 offset:4864
	ds_write_b32 v186, v22 offset:5120
	ds_write_b32 v186, v23 offset:5376
	ds_write_b32 v186, v24 offset:5632
	ds_write_b32 v186, v25 offset:5888
	ds_write_b32 v186, v26 offset:6144
	ds_write_b32 v186, v27 offset:6400
	ds_write_b32 v186, v28 offset:6656
	ds_write_b32 v186, v29 offset:6912
	ds_write_b32 v186, v30 offset:7168
	ds_write_b32 v186, v31 offset:7424
	ds_write_b32 v186, v32 offset:7680
	ds_write_b32 v186, v33 offset:7936
	ds_write_b32 v187, v126
	s_waitcnt lgkmcnt(0)
	s_barrier
	ds_read_b32 v66, v114 offset:0
	ds_read_b32 v67, v114 offset:256
	ds_read_b32 v68, v114 offset:512
	ds_read_b32 v69, v114 offset:768
	ds_read_b32 v70, v114 offset:1024
	ds_read_b32 v71, v114 offset:1280
	ds_read_b32 v72, v114 offset:1536
	ds_read_b32 v73, v114 offset:1792
	ds_read_b32 v74, v114 offset:2048
	ds_read_b32 v75, v114 offset:2304
	ds_read_b32 v76, v114 offset:2560
	ds_read_b32 v77, v114 offset:2816
	ds_read_b32 v78, v114 offset:3072
	ds_read_b32 v79, v114 offset:3328
	ds_read_b32 v80, v114 offset:3584
	ds_read_b32 v81, v114 offset:3840
	ds_read_b32 v82, v114 offset:4096
	ds_read_b32 v83, v114 offset:4352
	ds_read_b32 v84, v114 offset:4608
	ds_read_b32 v85, v114 offset:4864
	ds_read_b32 v86, v114 offset:5120
	ds_read_b32 v87, v114 offset:5376
	ds_read_b32 v88, v114 offset:5632
	ds_read_b32 v89, v114 offset:5888
	ds_read_b32 v90, v114 offset:6144
	ds_read_b32 v91, v114 offset:6400
	ds_read_b32 v92, v114 offset:6656
	ds_read_b32 v93, v114 offset:6912
	ds_read_b32 v94, v114 offset:7168
	ds_read_b32 v95, v114 offset:7424
	ds_read_b32 v96, v114 offset:7680
	ds_read_b32 v97, v114 offset:7936
	ds_read_b32 v178, v115
	s_waitcnt lgkmcnt(0)
; __device__ __forceinline__ int crow(int r,int hi){return (r&3)+8*(r>>2)+4*hi;}
; template<int MODE,int THRL,bool NOMAX> __device__ __forceinline__ void attn_unit(const bf16*Qs,const bf16*__restrict__ Ks,const bf16*__restrict__ Vs,bf16*Os,int S,int q0,float sink2,float slope2,float*ssq,char*shm,int tid_in){
;     ...
;   {auto rr=__builtin_amdgcn_permlane32_swap(__float_as_uint(l_reg),__float_as_uint(l_reg),false,false);l_reg=__uint_as_float(rr[0])+__uint_as_float(rr[1]);}
;   if(hi==0)wsf[32+r32]=l_reg;asm volatile("s_waitcnt lgkmcnt(0)":::"memory");
;   float rli[16];
;   #pragma unroll
;   for(int r=0;r<16;++r)rli[r]=LSM?__builtin_amdgcn_rcpf(lsum[r]):__builtin_amdgcn_rcpf(wsf[32+crow(r,hi)]);
;     ...
;   bf16*Ow=Os+(long)(q0+wid*QBLK)*OPITCH;
;   { bf16*stg=(bf16*)(shm+LDS_OST)+wid*2048;
;     #pragma unroll
;     for(int r=0;r<16;++r){const int orow=crow(r,hi);
;       #pragma unroll
;       for(int d0=0;d0<2;++d0)stg[orow*64+d0*32+r32]=__float2bfloat16(o[d0][r]*rli[r]);}
;     asm volatile("s_waitcnt lgkmcnt(0)":::"memory");
	v_add_f32_e32 v34, v34, v66
	v_add_f32_e32 v35, v35, v67
	v_add_f32_e32 v36, v36, v68
	v_add_f32_e32 v37, v37, v69
	v_add_f32_e32 v38, v38, v70
	v_add_f32_e32 v39, v39, v71
	v_add_f32_e32 v40, v40, v72
	v_add_f32_e32 v41, v41, v73
	v_add_f32_e32 v42, v42, v74
	v_add_f32_e32 v43, v43, v75
	v_add_f32_e32 v44, v44, v76
	v_add_f32_e32 v45, v45, v77
	v_add_f32_e32 v46, v46, v78
	v_add_f32_e32 v47, v47, v79
	v_add_f32_e32 v48, v48, v80
	v_add_f32_e32 v49, v49, v81
	v_add_f32_e32 v50, v50, v82
	v_add_f32_e32 v51, v51, v83
	v_add_f32_e32 v52, v52, v84
	v_add_f32_e32 v53, v53, v85
	v_add_f32_e32 v54, v54, v86
	v_add_f32_e32 v55, v55, v87
	v_add_f32_e32 v56, v56, v88
	v_add_f32_e32 v57, v57, v89
	v_add_f32_e32 v58, v58, v90
	v_add_f32_e32 v59, v59, v91
	v_add_f32_e32 v60, v60, v92
	v_add_f32_e32 v61, v61, v93
	v_add_f32_e32 v62, v62, v94
	v_add_f32_e32 v63, v63, v95
	v_add_f32_e32 v64, v64, v96
	v_add_f32_e32 v65, v65, v97
	v_add_f32_e32 v127, v127, v178
	v_and_b32_e32 v66, 31, v251
	v_and_b32_e32 v67, 63, v251
	v_lshrrev_b32_e32 v67, 5, v67
	s_lshl_b32 s10, s30, 8
	s_add_i32 s10, s10, 0x14000
	s_lshl_b32 s11, s30, 12
	s_add_i32 s11, s11, 0x14800
	v_and_b32_e32 v74, 63, v251
	v_lshrrev_b32_e32 v75, 3, v74
	v_and_b32_e32 v74, 7, v74
	v_lshlrev_b32_e32 v76, 4, v74
	v_lshl_add_u32 v76, v75, 7, v76
	v_add_u32_e32 v76, s11, v76
	v_lshlrev_b32_e32 v69, 9, v67
	v_lshl_add_u32 v69, v66, 1, v69
	v_add_u32_e32 v69, s11, v69
	v_lshl_add_u32 v68, v66, 2, s10
	v_mov_b32_e32 v70, v127
	s_nop 1
	v_permlane32_swap_b32_e32 v127, v70
	s_nop 1
	v_add_f32_e32 v70, v127, v70
	ds_write_b32 v68, v70 offset:128
	v_lshl_add_u32 v71, v67, 4, s10
	s_waitcnt lgkmcnt(0)
	ds_read_b128 v[82:85], v71 offset:128
	ds_read_b128 v[86:89], v71 offset:160
	ds_read_b128 v[90:93], v71 offset:192
	ds_read_b128 v[94:97], v71 offset:224
	s_waitcnt lgkmcnt(0)
	v_rcp_f32_e32 v82, v82
	v_rcp_f32_e32 v83, v83
	v_rcp_f32_e32 v84, v84
	v_rcp_f32_e32 v85, v85
	v_rcp_f32_e32 v86, v86
	v_rcp_f32_e32 v87, v87
	v_rcp_f32_e32 v88, v88
	v_rcp_f32_e32 v89, v89
	v_rcp_f32_e32 v90, v90
	v_rcp_f32_e32 v91, v91
	v_rcp_f32_e32 v92, v92
	v_rcp_f32_e32 v93, v93
	v_rcp_f32_e32 v94, v94
	v_rcp_f32_e32 v95, v95
	v_rcp_f32_e32 v96, v96
	v_rcp_f32_e32 v97, v97
	s_nop 0
	v_mul_f32_e32 v72, v34, v82
	v_cvt_pk_bf16_f32 v72, v72, v72
	ds_write_b16 v69, v72 offset:0
	v_mul_f32_e32 v73, v50, v82
	v_cvt_pk_bf16_f32 v73, v73, v73
	ds_write_b16 v69, v73 offset:64
	v_mul_f32_e32 v72, v35, v83
	v_cvt_pk_bf16_f32 v72, v72, v72
	ds_write_b16 v69, v72 offset:128
	v_mul_f32_e32 v73, v51, v83
	v_cvt_pk_bf16_f32 v73, v73, v73
	ds_write_b16 v69, v73 offset:192
	v_mul_f32_e32 v72, v36, v84
	v_cvt_pk_bf16_f32 v72, v72, v72
	ds_write_b16 v69, v72 offset:256
	v_mul_f32_e32 v73, v52, v84
	v_cvt_pk_bf16_f32 v73, v73, v73
	ds_write_b16 v69, v73 offset:320
	v_mul_f32_e32 v72, v37, v85
	v_cvt_pk_bf16_f32 v72, v72, v72
	ds_write_b16 v69, v72 offset:384
	v_mul_f32_e32 v73, v53, v85
	v_cvt_pk_bf16_f32 v73, v73, v73
	ds_write_b16 v69, v73 offset:448
	v_mul_f32_e32 v72, v38, v86
	v_cvt_pk_bf16_f32 v72, v72, v72
	ds_write_b16 v69, v72 offset:1024
	v_mul_f32_e32 v73, v54, v86
	v_cvt_pk_bf16_f32 v73, v73, v73
	ds_write_b16 v69, v73 offset:1088
	v_mul_f32_e32 v72, v39, v87
	v_cvt_pk_bf16_f32 v72, v72, v72
	ds_write_b16 v69, v72 offset:1152
	v_mul_f32_e32 v73, v55, v87
	v_cvt_pk_bf16_f32 v73, v73, v73
	ds_write_b16 v69, v73 offset:1216
	v_mul_f32_e32 v72, v40, v88
	v_cvt_pk_bf16_f32 v72, v72, v72
	ds_write_b16 v69, v72 offset:1280
	v_mul_f32_e32 v73, v56, v88
	v_cvt_pk_bf16_f32 v73, v73, v73
	ds_write_b16 v69, v73 offset:1344
	v_mul_f32_e32 v72, v41, v89
	v_cvt_pk_bf16_f32 v72, v72, v72
	ds_write_b16 v69, v72 offset:1408
	v_mul_f32_e32 v73, v57, v89
	v_cvt_pk_bf16_f32 v73, v73, v73
	ds_write_b16 v69, v73 offset:1472
	v_mul_f32_e32 v72, v42, v90
	v_cvt_pk_bf16_f32 v72, v72, v72
	ds_write_b16 v69, v72 offset:2048
	v_mul_f32_e32 v73, v58, v90
	v_cvt_pk_bf16_f32 v73, v73, v73
	ds_write_b16 v69, v73 offset:2112
	v_mul_f32_e32 v72, v43, v91
	v_cvt_pk_bf16_f32 v72, v72, v72
	ds_write_b16 v69, v72 offset:2176
	v_mul_f32_e32 v73, v59, v91
	v_cvt_pk_bf16_f32 v73, v73, v73
	ds_write_b16 v69, v73 offset:2240
	v_mul_f32_e32 v72, v44, v92
	v_cvt_pk_bf16_f32 v72, v72, v72
	ds_write_b16 v69, v72 offset:2304
	v_mul_f32_e32 v73, v60, v92
	v_cvt_pk_bf16_f32 v73, v73, v73
	ds_write_b16 v69, v73 offset:2368
	v_mul_f32_e32 v72, v45, v93
	v_cvt_pk_bf16_f32 v72, v72, v72
	ds_write_b16 v69, v72 offset:2432
	v_mul_f32_e32 v73, v61, v93
	v_cvt_pk_bf16_f32 v73, v73, v73
	ds_write_b16 v69, v73 offset:2496
	v_mul_f32_e32 v72, v46, v94
	v_cvt_pk_bf16_f32 v72, v72, v72
	ds_write_b16 v69, v72 offset:3072
	v_mul_f32_e32 v73, v62, v94
	v_cvt_pk_bf16_f32 v73, v73, v73
	ds_write_b16 v69, v73 offset:3136
	v_mul_f32_e32 v72, v47, v95
	v_cvt_pk_bf16_f32 v72, v72, v72
	ds_write_b16 v69, v72 offset:3200
	v_mul_f32_e32 v73, v63, v95
	v_cvt_pk_bf16_f32 v73, v73, v73
	ds_write_b16 v69, v73 offset:3264
	v_mul_f32_e32 v72, v48, v96
	v_cvt_pk_bf16_f32 v72, v72, v72
	ds_write_b16 v69, v72 offset:3328
	v_mul_f32_e32 v73, v64, v96
	v_cvt_pk_bf16_f32 v73, v73, v73
	ds_write_b16 v69, v73 offset:3392
	v_mul_f32_e32 v72, v49, v97
	v_cvt_pk_bf16_f32 v72, v72, v72
	ds_write_b16 v69, v72 offset:3456
	v_mul_f32_e32 v73, v65, v97
	v_cvt_pk_bf16_f32 v73, v73, v73
	ds_write_b16 v69, v73 offset:3520
	s_add_i32 s14, s4, 32
	s_mul_i32 s18, s14, 0x800
	s_mul_hi_i32 s19, s14, 0x800
	s_add_u32 s18, s48, s18
	s_addc_u32 s19, s49, s19
	s_mul_i32 s44, s14, 64
	s_mul_hi_i32 s45, s14, 64
	s_add_u32 s44, s26, s44
	s_addc_u32 s45, s27, s45
	v_lshlrev_b32_e32 v78, 11, v75
	v_lshl_add_u32 v78, v74, 4, v78
	v_lshlrev_b32_e32 v77, 6, v75
	v_cmp_eq_u32_e32 vcc, 0, v74
	s_waitcnt lgkmcnt(0)
; #define lane ({ int l_ = (int)__builtin_amdgcn_mbcnt_hi(~0u, __builtin_amdgcn_mbcnt_lo(~0u, 0u)); asm volatile("" : "+v"(l_)); l_; })
; template<int MODE,int THRL,bool NOMAX> __device__ __forceinline__ void attn_unit(const bf16*Qs,const bf16*__restrict__ Ks,const bf16*__restrict__ Vs,bf16*Os,int S,int q0,float sink2,float slope2,float*ssq,char*shm,int tid_in){
;     ...
;     #pragma unroll
;     for(int i=0;i<4;++i){const int row=i*8+(lane>>3),ch=lane&7; const u32x4 v=*(const u32x4*)(stg+row*64+ch*8); ATTN_STORE16(Ow+(long)row*OPITCH+ch*8,v);
;       float sq=0.f;
;       #pragma unroll
;       for(int k=0;k<4;++k){const float a=__uint_as_float(v[k]<<16),b=__uint_as_float(v[k]&0xffff0000u); sq+=a*a+b*b;}
;       sq+=__shfl_xor(sq,1); sq+=__shfl_xor(sq,2); sq+=__shfl_xor(sq,4);
;       if(ch==0)ssq[(long)(q0+wid*QBLK+row)*16]=sq;} }
	ds_read_b128 v[98:101], v76 offset:0
	ds_read_b128 v[102:105], v76 offset:1024
	ds_read_b128 v[106:109], v76 offset:2048
	ds_read_b128 v[110:113], v76 offset:3072
	s_waitcnt lgkmcnt(3)
	global_store_dwordx4 v78, v[98:101], s[18:19] offset:0
	v_and_b32_e32 v72, 0xffff0000, v98
	v_lshlrev_b32_e32 v73, 16, v98
	v_mul_f32_e32 v72, v72, v72
	v_fmac_f32_e32 v72, v73, v73
	v_mov_b32_e32 v130, v72
	v_and_b32_e32 v72, 0xffff0000, v99
	v_lshlrev_b32_e32 v73, 16, v99
	v_mul_f32_e32 v72, v72, v72
	v_fmac_f32_e32 v72, v73, v73
	v_add_f32_e32 v130, v130, v72
	v_and_b32_e32 v72, 0xffff0000, v100
	v_lshlrev_b32_e32 v73, 16, v100
	v_mul_f32_e32 v72, v72, v72
	v_fmac_f32_e32 v72, v73, v73
	v_add_f32_e32 v130, v72, v130
	v_and_b32_e32 v72, 0xffff0000, v101
	v_lshlrev_b32_e32 v73, 16, v101
	v_mul_f32_e32 v72, v72, v72
	v_fmac_f32_e32 v72, v73, v73
	v_add_f32_e32 v130, v72, v130
	v_add_u32_e32 v78, 0x4000, v78
	s_waitcnt lgkmcnt(2)
	global_store_dwordx4 v78, v[102:105], s[18:19]
	v_and_b32_e32 v72, 0xffff0000, v102
	v_lshlrev_b32_e32 v73, 16, v102
	v_mul_f32_e32 v72, v72, v72
	v_fmac_f32_e32 v72, v73, v73
	v_mov_b32_e32 v131, v72
	v_and_b32_e32 v72, 0xffff0000, v103
	v_lshlrev_b32_e32 v73, 16, v103
	v_mul_f32_e32 v72, v72, v72
	v_fmac_f32_e32 v72, v73, v73
	v_add_f32_e32 v131, v131, v72
	v_and_b32_e32 v72, 0xffff0000, v104
	v_lshlrev_b32_e32 v73, 16, v104
	v_mul_f32_e32 v72, v72, v72
	v_fmac_f32_e32 v72, v73, v73
	v_add_f32_e32 v131, v72, v131
	v_and_b32_e32 v72, 0xffff0000, v105
	v_lshlrev_b32_e32 v73, 16, v105
	v_mul_f32_e32 v72, v72, v72
	v_fmac_f32_e32 v72, v73, v73
	v_add_f32_e32 v131, v72, v131
	v_add_u32_e32 v78, 0x4000, v78
	s_waitcnt lgkmcnt(1)
	global_store_dwordx4 v78, v[106:109], s[18:19]
	v_and_b32_e32 v72, 0xffff0000, v106
	v_lshlrev_b32_e32 v73, 16, v106
	v_mul_f32_e32 v72, v72, v72
	v_fmac_f32_e32 v72, v73, v73
	v_mov_b32_e32 v132, v72
	v_and_b32_e32 v72, 0xffff0000, v107
	v_lshlrev_b32_e32 v73, 16, v107
	v_mul_f32_e32 v72, v72, v72
	v_fmac_f32_e32 v72, v73, v73
	v_add_f32_e32 v132, v132, v72
	v_and_b32_e32 v72, 0xffff0000, v108
	v_lshlrev_b32_e32 v73, 16, v108
	v_mul_f32_e32 v72, v72, v72
	v_fmac_f32_e32 v72, v73, v73
	v_add_f32_e32 v132, v72, v132
	v_and_b32_e32 v72, 0xffff0000, v109
	v_lshlrev_b32_e32 v73, 16, v109
	v_mul_f32_e32 v72, v72, v72
	v_fmac_f32_e32 v72, v73, v73
	v_add_f32_e32 v132, v72, v132
	v_add_u32_e32 v78, 0x4000, v78
	s_waitcnt lgkmcnt(0)
	global_store_dwordx4 v78, v[110:113], s[18:19]
	v_and_b32_e32 v72, 0xffff0000, v110
	v_lshlrev_b32_e32 v73, 16, v110
	v_mul_f32_e32 v72, v72, v72
	v_fmac_f32_e32 v72, v73, v73
	v_mov_b32_e32 v133, v72
	v_and_b32_e32 v72, 0xffff0000, v111
	v_lshlrev_b32_e32 v73, 16, v111
	v_mul_f32_e32 v72, v72, v72
	v_fmac_f32_e32 v72, v73, v73
	v_add_f32_e32 v133, v133, v72
	v_and_b32_e32 v72, 0xffff0000, v112
	v_lshlrev_b32_e32 v73, 16, v112
	v_mul_f32_e32 v72, v72, v72
	v_fmac_f32_e32 v72, v73, v73
	v_add_f32_e32 v133, v72, v133
	v_and_b32_e32 v72, 0xffff0000, v113
	v_lshlrev_b32_e32 v73, 16, v113
	v_mul_f32_e32 v72, v72, v72
	v_fmac_f32_e32 v72, v73, v73
	v_add_f32_e32 v133, v72, v133
	ds_bpermute_b32 v134, v239, v130
	ds_bpermute_b32 v135, v239, v131
	ds_bpermute_b32 v136, v239, v132
	ds_bpermute_b32 v137, v239, v133
	s_waitcnt lgkmcnt(0)
	v_add_f32_e32 v130, v130, v134
	v_add_f32_e32 v131, v131, v135
	v_add_f32_e32 v132, v132, v136
	v_add_f32_e32 v133, v133, v137
	ds_bpermute_b32 v134, v240, v130
	ds_bpermute_b32 v135, v240, v131
	ds_bpermute_b32 v136, v240, v132
	ds_bpermute_b32 v137, v240, v133
	s_waitcnt lgkmcnt(0)
	v_add_f32_e32 v130, v130, v134
	v_add_f32_e32 v131, v131, v135
	v_add_f32_e32 v132, v132, v136
	v_add_f32_e32 v133, v133, v137
	ds_bpermute_b32 v134, v241, v130
	ds_bpermute_b32 v135, v241, v131
	ds_bpermute_b32 v136, v241, v132
	ds_bpermute_b32 v137, v241, v133
	s_waitcnt lgkmcnt(0)
	v_add_f32_e32 v130, v130, v134
	v_add_f32_e32 v131, v131, v135
	v_add_f32_e32 v132, v132, v136
	v_add_f32_e32 v133, v133, v137
	s_nop 3
	s_and_saveexec_b64 s[10:11], vcc
	global_store_dword v77, v130, s[44:45]
	global_store_dword v77, v131, s[44:45] offset:512
	global_store_dword v77, v132, s[44:45] offset:1024
	global_store_dword v77, v133, s[44:45] offset:1536
	s_or_b64 exec, exec, s[10:11]
	s_branch .Lkvs_done
.Lkvs_fin0:
	ds_write_b32 v186, v34 offset:0
	ds_write_b32 v186, v35 offset:256
	ds_write_b32 v186, v36 offset:512
	ds_write_b32 v186, v37 offset:768
	ds_write_b32 v186, v38 offset:1024
	ds_write_b32 v186, v39 offset:1280
	ds_write_b32 v186, v40 offset:1536
	ds_write_b32 v186, v41 offset:1792
	ds_write_b32 v186, v42 offset:2048
	ds_write_b32 v186, v43 offset:2304
	ds_write_b32 v186, v44 offset:2560
	ds_write_b32 v186, v45 offset:2816
	ds_write_b32 v186, v46 offset:3072
	ds_write_b32 v186, v47 offset:3328
	ds_write_b32 v186, v48 offset:3584
	ds_write_b32 v186, v49 offset:3840
	ds_write_b32 v186, v50 offset:4096
	ds_write_b32 v186, v51 offset:4352
	ds_write_b32 v186, v52 offset:4608
	ds_write_b32 v186, v53 offset:4864
	ds_write_b32 v186, v54 offset:5120
	ds_write_b32 v186, v55 offset:5376
	ds_write_b32 v186, v56 offset:5632
	ds_write_b32 v186, v57 offset:5888
	ds_write_b32 v186, v58 offset:6144
	ds_write_b32 v186, v59 offset:6400
	ds_write_b32 v186, v60 offset:6656
	ds_write_b32 v186, v61 offset:6912
	ds_write_b32 v186, v62 offset:7168
	ds_write_b32 v186, v63 offset:7424
	ds_write_b32 v186, v64 offset:7680
	ds_write_b32 v186, v65 offset:7936
	ds_write_b32 v187, v127
	s_waitcnt lgkmcnt(0)
	s_barrier
; __device__ __forceinline__ int crow(int r,int hi){return (r&3)+8*(r>>2)+4*hi;}
; template<int MODE,int THRL,bool NOMAX> __device__ __forceinline__ void attn_unit(const bf16*Qs,const bf16*__restrict__ Ks,const bf16*__restrict__ Vs,bf16*Os,int S,int q0,float sink2,float slope2,float*ssq,char*shm,int tid_in){
;     ...
;   {auto rr=__builtin_amdgcn_permlane32_swap(__float_as_uint(l_reg),__float_as_uint(l_reg),false,false);l_reg=__uint_as_float(rr[0])+__uint_as_float(rr[1]);}
;   if(hi==0)wsf[32+r32]=l_reg;asm volatile("s_waitcnt lgkmcnt(0)":::"memory");
;   float rli[16];
;   #pragma unroll
;   for(int r=0;r<16;++r)rli[r]=LSM?__builtin_amdgcn_rcpf(lsum[r]):__builtin_amdgcn_rcpf(wsf[32+crow(r,hi)]);
;     ...
;   bf16*Ow=Os+(long)(q0+wid*QBLK)*OPITCH;
;   { bf16*stg=(bf16*)(shm+LDS_OST)+wid*2048;
;     #pragma unroll
;     for(int r=0;r<16;++r){const int orow=crow(r,hi);
;       #pragma unroll
;       for(int d0=0;d0<2;++d0)stg[orow*64+d0*32+r32]=__float2bfloat16(o[d0][r]*rli[r]);}
;     asm volatile("s_waitcnt lgkmcnt(0)":::"memory");
	ds_read_b32 v66, v114 offset:0
	ds_read_b32 v67, v114 offset:256
	ds_read_b32 v68, v114 offset:512
	ds_read_b32 v69, v114 offset:768
	ds_read_b32 v70, v114 offset:1024
	ds_read_b32 v71, v114 offset:1280
	ds_read_b32 v72, v114 offset:1536
	ds_read_b32 v73, v114 offset:1792
	ds_read_b32 v74, v114 offset:2048
	ds_read_b32 v75, v114 offset:2304
	ds_read_b32 v76, v114 offset:2560
	ds_read_b32 v77, v114 offset:2816
	ds_read_b32 v78, v114 offset:3072
	ds_read_b32 v79, v114 offset:3328
	ds_read_b32 v80, v114 offset:3584
	ds_read_b32 v81, v114 offset:3840
	ds_read_b32 v82, v114 offset:4096
	ds_read_b32 v83, v114 offset:4352
	ds_read_b32 v84, v114 offset:4608
	ds_read_b32 v85, v114 offset:4864
	ds_read_b32 v86, v114 offset:5120
	ds_read_b32 v87, v114 offset:5376
	ds_read_b32 v88, v114 offset:5632
	ds_read_b32 v89, v114 offset:5888
	ds_read_b32 v90, v114 offset:6144
	ds_read_b32 v91, v114 offset:6400
	ds_read_b32 v92, v114 offset:6656
	ds_read_b32 v93, v114 offset:6912
	ds_read_b32 v94, v114 offset:7168
	ds_read_b32 v95, v114 offset:7424
	ds_read_b32 v96, v114 offset:7680
	ds_read_b32 v97, v114 offset:7936
	ds_read_b32 v178, v115
	s_waitcnt lgkmcnt(0)
	v_add_f32_e32 v2, v2, v66
	v_add_f32_e32 v3, v3, v67
	v_add_f32_e32 v4, v4, v68
	v_add_f32_e32 v5, v5, v69
	v_add_f32_e32 v6, v6, v70
	v_add_f32_e32 v7, v7, v71
	v_add_f32_e32 v8, v8, v72
	v_add_f32_e32 v9, v9, v73
	v_add_f32_e32 v10, v10, v74
	v_add_f32_e32 v11, v11, v75
	v_add_f32_e32 v12, v12, v76
	v_add_f32_e32 v13, v13, v77
	v_add_f32_e32 v14, v14, v78
	v_add_f32_e32 v15, v15, v79
	v_add_f32_e32 v16, v16, v80
	v_add_f32_e32 v17, v17, v81
	v_add_f32_e32 v18, v18, v82
	v_add_f32_e32 v19, v19, v83
	v_add_f32_e32 v20, v20, v84
	v_add_f32_e32 v21, v21, v85
	v_add_f32_e32 v22, v22, v86
	v_add_f32_e32 v23, v23, v87
	v_add_f32_e32 v24, v24, v88
	v_add_f32_e32 v25, v25, v89
	v_add_f32_e32 v26, v26, v90
	v_add_f32_e32 v27, v27, v91
	v_add_f32_e32 v28, v28, v92
	v_add_f32_e32 v29, v29, v93
	v_add_f32_e32 v30, v30, v94
	v_add_f32_e32 v31, v31, v95
	v_add_f32_e32 v32, v32, v96
	v_add_f32_e32 v33, v33, v97
	v_add_f32_e32 v126, v126, v178
	v_and_b32_e32 v66, 31, v251
	v_and_b32_e32 v67, 63, v251
	v_lshrrev_b32_e32 v67, 5, v67
	s_lshl_b32 s10, s30, 8
	s_add_i32 s10, s10, 0x14000
	s_lshl_b32 s11, s30, 12
	s_add_i32 s11, s11, 0x14800
	v_and_b32_e32 v74, 63, v251
	v_lshrrev_b32_e32 v75, 3, v74
	v_and_b32_e32 v74, 7, v74
	v_lshlrev_b32_e32 v76, 4, v74
	v_lshl_add_u32 v76, v75, 7, v76
	v_add_u32_e32 v76, s11, v76
	v_lshlrev_b32_e32 v69, 9, v67
	v_lshl_add_u32 v69, v66, 1, v69
	v_add_u32_e32 v69, s11, v69
	v_lshl_add_u32 v68, v66, 2, s10
	v_mov_b32_e32 v70, v126
	s_nop 1
	v_permlane32_swap_b32_e32 v126, v70
	s_nop 1
	v_add_f32_e32 v70, v126, v70
	ds_write_b32 v68, v70 offset:128
	v_lshl_add_u32 v71, v67, 4, s10
	s_waitcnt lgkmcnt(0)
	ds_read_b128 v[82:85], v71 offset:128
	ds_read_b128 v[86:89], v71 offset:160
	ds_read_b128 v[90:93], v71 offset:192
	ds_read_b128 v[94:97], v71 offset:224
	s_waitcnt lgkmcnt(0)
	v_rcp_f32_e32 v82, v82
	v_rcp_f32_e32 v83, v83
	v_rcp_f32_e32 v84, v84
	v_rcp_f32_e32 v85, v85
	v_rcp_f32_e32 v86, v86
	v_rcp_f32_e32 v87, v87
	v_rcp_f32_e32 v88, v88
	v_rcp_f32_e32 v89, v89
	v_rcp_f32_e32 v90, v90
	v_rcp_f32_e32 v91, v91
	v_rcp_f32_e32 v92, v92
	v_rcp_f32_e32 v93, v93
	v_rcp_f32_e32 v94, v94
	v_rcp_f32_e32 v95, v95
	v_rcp_f32_e32 v96, v96
	v_rcp_f32_e32 v97, v97
	s_nop 0
	v_mul_f32_e32 v72, v2, v82
	v_cvt_pk_bf16_f32 v72, v72, v72
	ds_write_b16 v69, v72 offset:0
	v_mul_f32_e32 v73, v18, v82
	v_cvt_pk_bf16_f32 v73, v73, v73
	ds_write_b16 v69, v73 offset:64
	v_mul_f32_e32 v72, v3, v83
	v_cvt_pk_bf16_f32 v72, v72, v72
	ds_write_b16 v69, v72 offset:128
	v_mul_f32_e32 v73, v19, v83
	v_cvt_pk_bf16_f32 v73, v73, v73
	ds_write_b16 v69, v73 offset:192
	v_mul_f32_e32 v72, v4, v84
	v_cvt_pk_bf16_f32 v72, v72, v72
	ds_write_b16 v69, v72 offset:256
	v_mul_f32_e32 v73, v20, v84
	v_cvt_pk_bf16_f32 v73, v73, v73
	ds_write_b16 v69, v73 offset:320
	v_mul_f32_e32 v72, v5, v85
	v_cvt_pk_bf16_f32 v72, v72, v72
	ds_write_b16 v69, v72 offset:384
	v_mul_f32_e32 v73, v21, v85
	v_cvt_pk_bf16_f32 v73, v73, v73
	ds_write_b16 v69, v73 offset:448
	v_mul_f32_e32 v72, v6, v86
	v_cvt_pk_bf16_f32 v72, v72, v72
	ds_write_b16 v69, v72 offset:1024
	v_mul_f32_e32 v73, v22, v86
	v_cvt_pk_bf16_f32 v73, v73, v73
	ds_write_b16 v69, v73 offset:1088
	v_mul_f32_e32 v72, v7, v87
	v_cvt_pk_bf16_f32 v72, v72, v72
	ds_write_b16 v69, v72 offset:1152
	v_mul_f32_e32 v73, v23, v87
	v_cvt_pk_bf16_f32 v73, v73, v73
	ds_write_b16 v69, v73 offset:1216
	v_mul_f32_e32 v72, v8, v88
	v_cvt_pk_bf16_f32 v72, v72, v72
	ds_write_b16 v69, v72 offset:1280
	v_mul_f32_e32 v73, v24, v88
	v_cvt_pk_bf16_f32 v73, v73, v73
	ds_write_b16 v69, v73 offset:1344
	v_mul_f32_e32 v72, v9, v89
	v_cvt_pk_bf16_f32 v72, v72, v72
	ds_write_b16 v69, v72 offset:1408
	v_mul_f32_e32 v73, v25, v89
	v_cvt_pk_bf16_f32 v73, v73, v73
	ds_write_b16 v69, v73 offset:1472
	v_mul_f32_e32 v72, v10, v90
	v_cvt_pk_bf16_f32 v72, v72, v72
	ds_write_b16 v69, v72 offset:2048
	v_mul_f32_e32 v73, v26, v90
	v_cvt_pk_bf16_f32 v73, v73, v73
	ds_write_b16 v69, v73 offset:2112
	v_mul_f32_e32 v72, v11, v91
	v_cvt_pk_bf16_f32 v72, v72, v72
	ds_write_b16 v69, v72 offset:2176
	v_mul_f32_e32 v73, v27, v91
	v_cvt_pk_bf16_f32 v73, v73, v73
	ds_write_b16 v69, v73 offset:2240
	v_mul_f32_e32 v72, v12, v92
	v_cvt_pk_bf16_f32 v72, v72, v72
	ds_write_b16 v69, v72 offset:2304
	v_mul_f32_e32 v73, v28, v92
	v_cvt_pk_bf16_f32 v73, v73, v73
	ds_write_b16 v69, v73 offset:2368
	v_mul_f32_e32 v72, v13, v93
	v_cvt_pk_bf16_f32 v72, v72, v72
	ds_write_b16 v69, v72 offset:2432
	v_mul_f32_e32 v73, v29, v93
	v_cvt_pk_bf16_f32 v73, v73, v73
	ds_write_b16 v69, v73 offset:2496
	v_mul_f32_e32 v72, v14, v94
	v_cvt_pk_bf16_f32 v72, v72, v72
	ds_write_b16 v69, v72 offset:3072
	v_mul_f32_e32 v73, v30, v94
	v_cvt_pk_bf16_f32 v73, v73, v73
	ds_write_b16 v69, v73 offset:3136
	v_mul_f32_e32 v72, v15, v95
	v_cvt_pk_bf16_f32 v72, v72, v72
	ds_write_b16 v69, v72 offset:3200
	v_mul_f32_e32 v73, v31, v95
	v_cvt_pk_bf16_f32 v73, v73, v73
	ds_write_b16 v69, v73 offset:3264
	v_mul_f32_e32 v72, v16, v96
	v_cvt_pk_bf16_f32 v72, v72, v72
	ds_write_b16 v69, v72 offset:3328
	v_mul_f32_e32 v73, v32, v96
	v_cvt_pk_bf16_f32 v73, v73, v73
	ds_write_b16 v69, v73 offset:3392
	v_mul_f32_e32 v72, v17, v97
	v_cvt_pk_bf16_f32 v72, v72, v72
	ds_write_b16 v69, v72 offset:3456
	v_mul_f32_e32 v73, v33, v97
	v_cvt_pk_bf16_f32 v73, v73, v73
	ds_write_b16 v69, v73 offset:3520
	s_add_i32 s14, s4, 0
	s_mul_i32 s18, s14, 0x800
	s_mul_hi_i32 s19, s14, 0x800
	s_add_u32 s18, s48, s18
	s_addc_u32 s19, s49, s19
	s_mul_i32 s44, s14, 64
	s_mul_hi_i32 s45, s14, 64
	s_add_u32 s44, s26, s44
	s_addc_u32 s45, s27, s45
	v_lshlrev_b32_e32 v78, 11, v75
	v_lshl_add_u32 v78, v74, 4, v78
	v_lshlrev_b32_e32 v77, 6, v75
	v_cmp_eq_u32_e32 vcc, 0, v74
	s_waitcnt lgkmcnt(0)
; #define lane ({ int l_ = (int)__builtin_amdgcn_mbcnt_hi(~0u, __builtin_amdgcn_mbcnt_lo(~0u, 0u)); asm volatile("" : "+v"(l_)); l_; })
; template<int MODE,int THRL,bool NOMAX> __device__ __forceinline__ void attn_unit(const bf16*Qs,const bf16*__restrict__ Ks,const bf16*__restrict__ Vs,bf16*Os,int S,int q0,float sink2,float slope2,float*ssq,char*shm,int tid_in){
;     ...
;     #pragma unroll
;     for(int i=0;i<4;++i){const int row=i*8+(lane>>3),ch=lane&7; const u32x4 v=*(const u32x4*)(stg+row*64+ch*8); ATTN_STORE16(Ow+(long)row*OPITCH+ch*8,v);
;       float sq=0.f;
;       #pragma unroll
;       for(int k=0;k<4;++k){const float a=__uint_as_float(v[k]<<16),b=__uint_as_float(v[k]&0xffff0000u); sq+=a*a+b*b;}
;       sq+=__shfl_xor(sq,1); sq+=__shfl_xor(sq,2); sq+=__shfl_xor(sq,4);
;       if(ch==0)ssq[(long)(q0+wid*QBLK+row)*16]=sq;} }
	ds_read_b128 v[98:101], v76 offset:0
	ds_read_b128 v[102:105], v76 offset:1024
	ds_read_b128 v[106:109], v76 offset:2048
	ds_read_b128 v[110:113], v76 offset:3072
	s_waitcnt lgkmcnt(3)
	global_store_dwordx4 v78, v[98:101], s[18:19] offset:0
	v_and_b32_e32 v72, 0xffff0000, v98
	v_lshlrev_b32_e32 v73, 16, v98
	v_mul_f32_e32 v72, v72, v72
	v_fmac_f32_e32 v72, v73, v73
	v_mov_b32_e32 v130, v72
	v_and_b32_e32 v72, 0xffff0000, v99
	v_lshlrev_b32_e32 v73, 16, v99
	v_mul_f32_e32 v72, v72, v72
	v_fmac_f32_e32 v72, v73, v73
	v_add_f32_e32 v130, v130, v72
	v_and_b32_e32 v72, 0xffff0000, v100
	v_lshlrev_b32_e32 v73, 16, v100
	v_mul_f32_e32 v72, v72, v72
	v_fmac_f32_e32 v72, v73, v73
	v_add_f32_e32 v130, v72, v130
	v_and_b32_e32 v72, 0xffff0000, v101
	v_lshlrev_b32_e32 v73, 16, v101
	v_mul_f32_e32 v72, v72, v72
	v_fmac_f32_e32 v72, v73, v73
	v_add_f32_e32 v130, v72, v130
	v_add_u32_e32 v78, 0x4000, v78
	s_waitcnt lgkmcnt(2)
	global_store_dwordx4 v78, v[102:105], s[18:19]
	v_and_b32_e32 v72, 0xffff0000, v102
	v_lshlrev_b32_e32 v73, 16, v102
	v_mul_f32_e32 v72, v72, v72
	v_fmac_f32_e32 v72, v73, v73
	v_mov_b32_e32 v131, v72
	v_and_b32_e32 v72, 0xffff0000, v103
	v_lshlrev_b32_e32 v73, 16, v103
	v_mul_f32_e32 v72, v72, v72
	v_fmac_f32_e32 v72, v73, v73
	v_add_f32_e32 v131, v131, v72
	v_and_b32_e32 v72, 0xffff0000, v104
	v_lshlrev_b32_e32 v73, 16, v104
	v_mul_f32_e32 v72, v72, v72
	v_fmac_f32_e32 v72, v73, v73
	v_add_f32_e32 v131, v72, v131
	v_and_b32_e32 v72, 0xffff0000, v105
	v_lshlrev_b32_e32 v73, 16, v105
	v_mul_f32_e32 v72, v72, v72
	v_fmac_f32_e32 v72, v73, v73
	v_add_f32_e32 v131, v72, v131
	v_add_u32_e32 v78, 0x4000, v78
	s_waitcnt lgkmcnt(1)
	global_store_dwordx4 v78, v[106:109], s[18:19]
	v_and_b32_e32 v72, 0xffff0000, v106
	v_lshlrev_b32_e32 v73, 16, v106
	v_mul_f32_e32 v72, v72, v72
	v_fmac_f32_e32 v72, v73, v73
	v_mov_b32_e32 v132, v72
	v_and_b32_e32 v72, 0xffff0000, v107
	v_lshlrev_b32_e32 v73, 16, v107
	v_mul_f32_e32 v72, v72, v72
	v_fmac_f32_e32 v72, v73, v73
	v_add_f32_e32 v132, v132, v72
	v_and_b32_e32 v72, 0xffff0000, v108
	v_lshlrev_b32_e32 v73, 16, v108
	v_mul_f32_e32 v72, v72, v72
	v_fmac_f32_e32 v72, v73, v73
	v_add_f32_e32 v132, v72, v132
	v_and_b32_e32 v72, 0xffff0000, v109
	v_lshlrev_b32_e32 v73, 16, v109
	v_mul_f32_e32 v72, v72, v72
	v_fmac_f32_e32 v72, v73, v73
	v_add_f32_e32 v132, v72, v132
	v_add_u32_e32 v78, 0x4000, v78
	s_waitcnt lgkmcnt(0)
	global_store_dwordx4 v78, v[110:113], s[18:19]
	v_and_b32_e32 v72, 0xffff0000, v110
	v_lshlrev_b32_e32 v73, 16, v110
	v_mul_f32_e32 v72, v72, v72
	v_fmac_f32_e32 v72, v73, v73
	v_mov_b32_e32 v133, v72
	v_and_b32_e32 v72, 0xffff0000, v111
	v_lshlrev_b32_e32 v73, 16, v111
	v_mul_f32_e32 v72, v72, v72
	v_fmac_f32_e32 v72, v73, v73
	v_add_f32_e32 v133, v133, v72
	v_and_b32_e32 v72, 0xffff0000, v112
	v_lshlrev_b32_e32 v73, 16, v112
	v_mul_f32_e32 v72, v72, v72
	v_fmac_f32_e32 v72, v73, v73
	v_add_f32_e32 v133, v72, v133
	v_and_b32_e32 v72, 0xffff0000, v113
	v_lshlrev_b32_e32 v73, 16, v113
	v_mul_f32_e32 v72, v72, v72
	v_fmac_f32_e32 v72, v73, v73
	v_add_f32_e32 v133, v72, v133
	ds_bpermute_b32 v134, v239, v130
	ds_bpermute_b32 v135, v239, v131
	ds_bpermute_b32 v136, v239, v132
	ds_bpermute_b32 v137, v239, v133
	s_waitcnt lgkmcnt(0)
	v_add_f32_e32 v130, v130, v134
	v_add_f32_e32 v131, v131, v135
	v_add_f32_e32 v132, v132, v136
	v_add_f32_e32 v133, v133, v137
	ds_bpermute_b32 v134, v240, v130
	ds_bpermute_b32 v135, v240, v131
	ds_bpermute_b32 v136, v240, v132
	ds_bpermute_b32 v137, v240, v133
	s_waitcnt lgkmcnt(0)
	v_add_f32_e32 v130, v130, v134
	v_add_f32_e32 v131, v131, v135
	v_add_f32_e32 v132, v132, v136
	v_add_f32_e32 v133, v133, v137
	ds_bpermute_b32 v134, v241, v130
	ds_bpermute_b32 v135, v241, v131
	ds_bpermute_b32 v136, v241, v132
	ds_bpermute_b32 v137, v241, v133
	s_waitcnt lgkmcnt(0)
	v_add_f32_e32 v130, v130, v134
	v_add_f32_e32 v131, v131, v135
	v_add_f32_e32 v132, v132, v136
	v_add_f32_e32 v133, v133, v137
	s_nop 3
	s_and_saveexec_b64 s[10:11], vcc
	global_store_dword v77, v130, s[44:45]
	global_store_dword v77, v131, s[44:45] offset:512
	global_store_dword v77, v132, s[44:45] offset:1024
	global_store_dword v77, v133, s[44:45] offset:1536
	s_or_b64 exec, exec, s[10:11]
	s_branch .Lkvs_done
.Lkvs_done:
	s_mov_b64 s[10:11], exec
	s_branch .LBB0_388

;     __device__ __forceinline__ void prefetch(const Unit& u, int wr, int fr, float (&rsv)[2][4]) const {
;         unsigned lrow = (unsigned)(wr * 64 + fr); asm volatile("" : "+v"(lrow)); const float* rb = rsx + u.pm * BM;
; #pragma unroll
;         for (int ai = 0; ai < 2; ++ai)
; #pragma unroll
;             for (int m = 0; m < 4; ++m) rsv[ai][m] = rb[lrow + (unsigned)(ai * HALF + m * 16)];
;     }
; template <class Epi, class Sched, bool ALIGN_EPI = false, bool SP2 = false>
; __device__ __forceinline__ void gemm_phase(PG8_LAS unsigned char* lds, const Gemm g, const Sched& S, const Epi& E, int tid_in) {
;     ...
; #pragma unroll
;         for (int a = 0; a < 2; ++a)
; #pragma unroll
;             for (int b = 0; b < 2; ++b)
; #pragma unroll
;                 for (int m = 0; m < 4; ++m)
; #pragma unroll
;                     for (int n = 0; n < 2; ++n) acc[a][b][m][n] = (f32x4){0.f, 0.f, 0.f, 0.f};
.LBB0_790:
	s_lshl_b32 s100, s30, 10
	s_add_u32 s100, s57, s100
	s_addc_u32 s101, s58, 0
	v_lshlrev_b32_e32 v3, 2, v129
	global_load_dword v234, v3, s[100:101]
	global_load_dword v235, v3, s[100:101] offset:64
	global_load_dword v236, v3, s[100:101] offset:128
	global_load_dword v237, v3, s[100:101] offset:192
	global_load_dword v245, v3, s[100:101] offset:512
	global_load_dword v247, v3, s[100:101] offset:576
	global_load_dword v252, v3, s[100:101] offset:640
	global_load_dword v253, v3, s[100:101] offset:704
	s_ashr_i32 s25, s24, 31
	s_lshl_b64 s[26:27], s[24:25], 19
	s_add_u32 s26, s40, s26
	s_addc_u32 s27, s48, s27
	s_and_b64 s[28:29], s[36:37], exec
	s_cselect_b32 s25, s27, s39
	s_cselect_b32 s61, s26, s38
	s_ashr_i32 s19, s18, 31
	s_lshl_b64 s[28:29], s[18:19], 19
	s_add_u32 s28, s49, s28
	s_addc_u32 s29, s50, s29
	s_and_b64 s[44:45], s[36:37], exec
	s_cselect_b32 s19, s29, s81
	s_cselect_b32 s62, s28, s80
	s_add_u32 s63, s80, 0x100
	v_mov_b32_e32 v2, 0
	v_lshl_add_u64 v[144:145], s[38:39], 0, v[140:141]
	v_lshl_add_u64 v[146:147], s[38:39], 0, v[142:143]
	s_addc_u32 s64, s81, 0
	s_mov_b32 s65, -2
	s_mov_b64 s[80:81], 0
	v_mov_b32_e32 v3, v2
	v_mov_b32_e32 v4, v2
	v_mov_b32_e32 v5, v2
	v_mov_b32_e32 v10, v2
	v_mov_b32_e32 v11, v2
	v_mov_b32_e32 v12, v2
	v_mov_b32_e32 v13, v2
	v_mov_b32_e32 v18, v2
	v_mov_b32_e32 v19, v2
	v_mov_b32_e32 v20, v2
	v_mov_b32_e32 v21, v2
	v_mov_b32_e32 v26, v2
	v_mov_b32_e32 v27, v2
	v_mov_b32_e32 v28, v2
	v_mov_b32_e32 v29, v2
	v_mov_b32_e32 v34, v2
	v_mov_b32_e32 v35, v2
	v_mov_b32_e32 v36, v2
	v_mov_b32_e32 v37, v2
	v_mov_b32_e32 v42, v2
	v_mov_b32_e32 v43, v2
	v_mov_b32_e32 v44, v2
	v_mov_b32_e32 v45, v2
	v_mov_b32_e32 v50, v2
	v_mov_b32_e32 v51, v2
	v_mov_b32_e32 v52, v2
	v_mov_b32_e32 v53, v2
	v_mov_b32_e32 v58, v2
	v_mov_b32_e32 v59, v2
	v_mov_b32_e32 v60, v2
	v_mov_b32_e32 v61, v2
	v_mov_b32_e32 v6, v2
	v_mov_b32_e32 v7, v2
	v_mov_b32_e32 v8, v2
	v_mov_b32_e32 v9, v2
	v_mov_b32_e32 v14, v2
	v_mov_b32_e32 v15, v2
	v_mov_b32_e32 v16, v2
	v_mov_b32_e32 v17, v2
	v_mov_b32_e32 v22, v2
	v_mov_b32_e32 v23, v2
	v_mov_b32_e32 v24, v2
	v_mov_b32_e32 v25, v2
	v_mov_b32_e32 v30, v2
	v_mov_b32_e32 v31, v2
	v_mov_b32_e32 v32, v2
	v_mov_b32_e32 v33, v2
	v_mov_b32_e32 v38, v2
	v_mov_b32_e32 v39, v2
	v_mov_b32_e32 v40, v2
	v_mov_b32_e32 v41, v2
	v_mov_b32_e32 v46, v2
	v_mov_b32_e32 v47, v2
	v_mov_b32_e32 v48, v2
	v_mov_b32_e32 v49, v2
	v_mov_b32_e32 v54, v2
	v_mov_b32_e32 v55, v2
	v_mov_b32_e32 v56, v2
	v_mov_b32_e32 v57, v2
	v_mov_b32_e32 v62, v2
	v_mov_b32_e32 v63, v2
	v_mov_b32_e32 v64, v2
	v_mov_b32_e32 v65, v2
	v_mov_b32_e32 v66, v2
	v_mov_b32_e32 v67, v2
	v_mov_b32_e32 v68, v2
	v_mov_b32_e32 v69, v2
	v_mov_b32_e32 v74, v2
	v_mov_b32_e32 v75, v2
	v_mov_b32_e32 v76, v2
	v_mov_b32_e32 v77, v2
	v_mov_b32_e32 v82, v2
	v_mov_b32_e32 v83, v2
	v_mov_b32_e32 v84, v2
	v_mov_b32_e32 v85, v2
	v_mov_b32_e32 v90, v2
	v_mov_b32_e32 v91, v2
	v_mov_b32_e32 v92, v2
	v_mov_b32_e32 v93, v2
	v_mov_b32_e32 v98, v2
	v_mov_b32_e32 v99, v2
	v_mov_b32_e32 v100, v2
	v_mov_b32_e32 v101, v2
	v_mov_b32_e32 v106, v2
	v_mov_b32_e32 v107, v2
	v_mov_b32_e32 v108, v2
	v_mov_b32_e32 v109, v2
	v_mov_b32_e32 v114, v2
	v_mov_b32_e32 v115, v2
	v_mov_b32_e32 v116, v2
	v_mov_b32_e32 v117, v2
	v_mov_b32_e32 v122, v2
	v_mov_b32_e32 v123, v2
	v_mov_b32_e32 v124, v2
	v_mov_b32_e32 v125, v2
	v_mov_b32_e32 v70, v2
	v_mov_b32_e32 v71, v2
	v_mov_b32_e32 v72, v2
	v_mov_b32_e32 v73, v2
	v_mov_b32_e32 v78, v2
	v_mov_b32_e32 v79, v2
	v_mov_b32_e32 v80, v2
	v_mov_b32_e32 v81, v2
	v_mov_b32_e32 v86, v2
	v_mov_b32_e32 v87, v2
	v_mov_b32_e32 v88, v2
	v_mov_b32_e32 v89, v2
	v_mov_b32_e32 v94, v2
	v_mov_b32_e32 v95, v2
	v_mov_b32_e32 v96, v2
	v_mov_b32_e32 v97, v2
	v_mov_b32_e32 v102, v2
	v_mov_b32_e32 v103, v2
	v_mov_b32_e32 v104, v2
	v_mov_b32_e32 v105, v2
	v_mov_b32_e32 v110, v2
	v_mov_b32_e32 v111, v2
	v_mov_b32_e32 v112, v2
	v_mov_b32_e32 v113, v2
	v_mov_b32_e32 v118, v2
	v_mov_b32_e32 v119, v2
	v_mov_b32_e32 v120, v2
	v_mov_b32_e32 v121, v2
	v_mov_b32_e32 v130, v2
	v_mov_b32_e32 v131, v2
	v_mov_b32_e32 v132, v2
	v_mov_b32_e32 v133, v2

; __device__ __forceinline__ unsigned cvt_pk_bf16(float lo, float hi) { unsigned r; asm volatile("v_cvt_pk_bf16_f32 %0, %1, %2" : "=v"(r) : "v"(lo), "v"(hi)); return r; }
; __device__ __forceinline__ float silu_mul(float g, float u, float c1, float c2) { const float e = __builtin_amdgcn_exp2f(g * c1); return (g * u) * (c2 * __builtin_amdgcn_rcpf(1.0f + e)); }
;     __device__ __forceinline__ void operator()(const f32x4 (&acc)[2][2][4][2], const Unit& u, int wr, int wc, int fr, int fq) const {
;         const int row0 = u.pm * BM + wr * 64 + fr; const int col0 = u.pn * HALF + wc * 32 + 8 * fq;
;         float rsv[2][4]; prefetch(u, wr, fr, rsv);
; #pragma unroll
;         for (int ai = 0; ai < 2; ++ai)
; #pragma unroll
;             for (int m = 0; m < 4; ++m) { bf16_t* rowp = O + (size_t)(row0 + ai * HALF + m * 16) * ldc + col0;
;                 const float rs = rsv[ai][m], c1 = rs * -1.4426950408889634f, c2 = rs * rs; const f32x4 g0 = acc[ai][0][m][0], g1 = acc[ai][0][m][1], u0 = acc[ai][1][m][0], u1 = acc[ai][1][m][1];
;                 u32x4 w; w.x = cvt_pk_bf16(silu_mul(g0[0], u0[0], c1, c2), silu_mul(g0[1], u0[1], c1, c2)); w.y = cvt_pk_bf16(silu_mul(g0[2], u0[2], c1, c2), silu_mul(g0[3], u0[3], c1, c2));
;                 w.z = cvt_pk_bf16(silu_mul(g1[0], u1[0], c1, c2), silu_mul(g1[1], u1[1], c1, c2)); w.w = cvt_pk_bf16(silu_mul(g1[2], u1[2], c1, c2), silu_mul(g1[3], u1[3], c1, c2));
;                 *(u32x4*)rowp = w; }
.LBB0_794:
	s_lshl_b32 s30, s30, 8
	v_lshl_or_b32 v146, s31, 7, v153
	v_add_u32_e32 v155, s30, v129
	v_ashrrev_i32_e32 v147, 31, v146
	v_mov_b64_e32 v[144:145], s[10:11]
	s_movk_i32 s67, 0x3000
	s_mov_b64 s[84:85], 0x4c00000
	v_mad_i64_i32 v[148:149], s[30:31], v155, s33, v[144:145]
	v_lshlrev_b64 v[146:147], 1, v[146:147]
	s_nop 0
	v_lshl_add_u64 v[148:149], v[148:149], 0, v[146:147]
	s_waitcnt vmcnt(8)
	v_mul_f32_e32 v156, 0xbfb8aa3b, v234
	v_mul_f32_e32 v157, v234, v234
	v_mul_f32_e32 v158, v130, v156
	v_mul_f32_e32 v159, v131, v156
	v_mul_f32_e32 v160, v132, v156
	v_mul_f32_e32 v161, v133, v156
	v_mul_f32_e32 v162, v118, v156
	v_mul_f32_e32 v163, v119, v156
	v_mul_f32_e32 v164, v120, v156
	v_mul_f32_e32 v0, v121, v156
	v_exp_f32_e32 v158, v158
	v_exp_f32_e32 v159, v159
	v_exp_f32_e32 v160, v160
	v_exp_f32_e32 v161, v161
	v_exp_f32_e32 v162, v162
	v_exp_f32_e32 v163, v163
	v_exp_f32_e32 v164, v164
	v_exp_f32_e32 v0, v0
	v_mul_f32_e32 v122, v130, v122
	v_mul_f32_e32 v123, v131, v123
	v_mul_f32_e32 v124, v132, v124
	v_mul_f32_e32 v125, v133, v125
	v_mul_f32_e32 v114, v118, v114
	v_mul_f32_e32 v115, v119, v115
	v_mul_f32_e32 v116, v120, v116
	v_mul_f32_e32 v117, v121, v117
	v_add_f32_e32 v158, 1.0, v158
	v_add_f32_e32 v159, 1.0, v159
	v_add_f32_e32 v160, 1.0, v160
	v_add_f32_e32 v161, 1.0, v161
	v_add_f32_e32 v162, 1.0, v162
	v_add_f32_e32 v163, 1.0, v163
	v_add_f32_e32 v164, 1.0, v164
	v_add_f32_e32 v0, 1.0, v0
	v_rcp_f32_e32 v158, v158
	v_rcp_f32_e32 v159, v159
	v_rcp_f32_e32 v160, v160
	v_rcp_f32_e32 v161, v161
	v_rcp_f32_e32 v162, v162
	v_rcp_f32_e32 v163, v163
	v_rcp_f32_e32 v164, v164
	v_rcp_f32_e32 v0, v0
	v_mul_f32_e32 v158, v157, v158
	v_mul_f32_e32 v159, v157, v159
	v_mul_f32_e32 v160, v157, v160
	v_mul_f32_e32 v161, v157, v161
	v_mul_f32_e32 v162, v157, v162
	v_mul_f32_e32 v163, v157, v163
	v_mul_f32_e32 v164, v157, v164
	v_mul_f32_e32 v0, v157, v0
	v_mul_f32_e32 v130, v122, v158
	v_mul_f32_e32 v131, v123, v159
	v_mul_f32_e32 v132, v124, v160
	v_mul_f32_e32 v133, v125, v161
	v_mul_f32_e32 v118, v114, v162
	v_mul_f32_e32 v119, v115, v163
	v_mul_f32_e32 v120, v116, v164
	v_mul_f32_e32 v121, v117, v0
	v_cvt_pk_bf16_f32 v122, v130, v131
	v_cvt_pk_bf16_f32 v123, v132, v133
	v_cvt_pk_bf16_f32 v124, v118, v119
	v_cvt_pk_bf16_f32 v125, v120, v121
	global_store_dwordx4 v[148:149], v[122:125], off
	v_mul_f32_e32 v156, 0xbfb8aa3b, v235
	v_mul_f32_e32 v157, v235, v235
	v_mul_f32_e32 v158, v110, v156
	v_mul_f32_e32 v159, v111, v156
	v_mul_f32_e32 v160, v112, v156
	v_mul_f32_e32 v161, v113, v156
	v_mul_f32_e32 v162, v102, v156
	v_mul_f32_e32 v163, v103, v156
	v_mul_f32_e32 v164, v104, v156
	v_mul_f32_e32 v0, v105, v156
	v_exp_f32_e32 v158, v158
	v_exp_f32_e32 v159, v159
	v_exp_f32_e32 v160, v160
	v_exp_f32_e32 v161, v161
	v_exp_f32_e32 v162, v162
	v_exp_f32_e32 v163, v163
	v_exp_f32_e32 v164, v164
	v_exp_f32_e32 v0, v0
	v_mul_f32_e32 v106, v110, v106
	v_mul_f32_e32 v107, v111, v107
	v_mul_f32_e32 v108, v112, v108
	v_mul_f32_e32 v109, v113, v109
	v_mul_f32_e32 v98, v102, v98
	v_mul_f32_e32 v99, v103, v99
	v_mul_f32_e32 v100, v104, v100
	v_mul_f32_e32 v101, v105, v101
	v_add_f32_e32 v158, 1.0, v158
	v_add_f32_e32 v159, 1.0, v159
	v_add_f32_e32 v160, 1.0, v160
	v_add_f32_e32 v161, 1.0, v161
	v_add_f32_e32 v162, 1.0, v162
	v_add_f32_e32 v163, 1.0, v163
	v_add_f32_e32 v164, 1.0, v164
	v_add_f32_e32 v0, 1.0, v0
	v_rcp_f32_e32 v158, v158
	v_rcp_f32_e32 v159, v159
	v_rcp_f32_e32 v160, v160
	v_rcp_f32_e32 v161, v161
	v_rcp_f32_e32 v162, v162
	v_rcp_f32_e32 v163, v163
	v_rcp_f32_e32 v164, v164
	v_rcp_f32_e32 v0, v0
	v_mul_f32_e32 v158, v157, v158
	v_mul_f32_e32 v159, v157, v159
	v_mul_f32_e32 v160, v157, v160
	v_mul_f32_e32 v161, v157, v161
	v_mul_f32_e32 v162, v157, v162
	v_mul_f32_e32 v163, v157, v163
	v_mul_f32_e32 v164, v157, v164
	v_mul_f32_e32 v0, v157, v0
	v_mul_f32_e32 v110, v106, v158
	v_mul_f32_e32 v111, v107, v159
	v_mul_f32_e32 v112, v108, v160
	v_mul_f32_e32 v113, v109, v161
	v_mul_f32_e32 v102, v98, v162
	v_mul_f32_e32 v103, v99, v163
	v_mul_f32_e32 v104, v100, v164
	v_mul_f32_e32 v105, v101, v0
	v_cvt_pk_bf16_f32 v106, v110, v111
	v_cvt_pk_bf16_f32 v107, v112, v113
	v_cvt_pk_bf16_f32 v108, v102, v103
	v_cvt_pk_bf16_f32 v109, v104, v105
	s_mov_b64 s[100:101], 0x16000
	v_lshl_add_u64 v[150:151], v[148:149], 0, s[100:101]
	global_store_dwordx4 v[150:151], v[106:109], off
	v_mul_f32_e32 v156, 0xbfb8aa3b, v236
	v_mul_f32_e32 v157, v236, v236
	v_mul_f32_e32 v158, v94, v156
	v_mul_f32_e32 v159, v95, v156
	v_mul_f32_e32 v160, v96, v156
	v_mul_f32_e32 v161, v97, v156
	v_mul_f32_e32 v162, v86, v156
	v_mul_f32_e32 v163, v87, v156
	v_mul_f32_e32 v164, v88, v156
	v_mul_f32_e32 v0, v89, v156
	v_exp_f32_e32 v158, v158
	v_exp_f32_e32 v159, v159
	v_exp_f32_e32 v160, v160
	v_exp_f32_e32 v161, v161
	v_exp_f32_e32 v162, v162
	v_exp_f32_e32 v163, v163
	v_exp_f32_e32 v164, v164
	v_exp_f32_e32 v0, v0
	v_mul_f32_e32 v90, v94, v90
	v_mul_f32_e32 v91, v95, v91
	v_mul_f32_e32 v92, v96, v92
	v_mul_f32_e32 v93, v97, v93
	v_mul_f32_e32 v82, v86, v82
	v_mul_f32_e32 v83, v87, v83
	v_mul_f32_e32 v84, v88, v84
	v_mul_f32_e32 v85, v89, v85
	v_add_f32_e32 v158, 1.0, v158
	v_add_f32_e32 v159, 1.0, v159
	v_add_f32_e32 v160, 1.0, v160
	v_add_f32_e32 v161, 1.0, v161
	v_add_f32_e32 v162, 1.0, v162
	v_add_f32_e32 v163, 1.0, v163
	v_add_f32_e32 v164, 1.0, v164
	v_add_f32_e32 v0, 1.0, v0
	v_rcp_f32_e32 v158, v158
	v_rcp_f32_e32 v159, v159
	v_rcp_f32_e32 v160, v160
	v_rcp_f32_e32 v161, v161
	v_rcp_f32_e32 v162, v162
	v_rcp_f32_e32 v163, v163
	v_rcp_f32_e32 v164, v164
	v_rcp_f32_e32 v0, v0
	v_mul_f32_e32 v158, v157, v158
	v_mul_f32_e32 v159, v157, v159
	v_mul_f32_e32 v160, v157, v160
; __device__ __forceinline__ unsigned cvt_pk_bf16(float lo, float hi) { unsigned r; asm volatile("v_cvt_pk_bf16_f32 %0, %1, %2" : "=v"(r) : "v"(lo), "v"(hi)); return r; }
; __device__ __forceinline__ float silu_mul(float g, float u, float c1, float c2) { const float e = __builtin_amdgcn_exp2f(g * c1); return (g * u) * (c2 * __builtin_amdgcn_rcpf(1.0f + e)); }
;     __device__ __forceinline__ void operator()(const f32x4 (&acc)[2][2][4][2], const Unit& u, int wr, int wc, int fr, int fq) const {
;     ...
;             for (int m = 0; m < 4; ++m) { bf16_t* rowp = O + (size_t)(row0 + ai * HALF + m * 16) * ldc + col0;
;                 const float rs = rsv[ai][m], c1 = rs * -1.4426950408889634f, c2 = rs * rs; const f32x4 g0 = acc[ai][0][m][0], g1 = acc[ai][0][m][1], u0 = acc[ai][1][m][0], u1 = acc[ai][1][m][1];
;                 u32x4 w; w.x = cvt_pk_bf16(silu_mul(g0[0], u0[0], c1, c2), silu_mul(g0[1], u0[1], c1, c2)); w.y = cvt_pk_bf16(silu_mul(g0[2], u0[2], c1, c2), silu_mul(g0[3], u0[3], c1, c2));
;                 w.z = cvt_pk_bf16(silu_mul(g1[0], u1[0], c1, c2), silu_mul(g1[1], u1[1], c1, c2)); w.w = cvt_pk_bf16(silu_mul(g1[2], u1[2], c1, c2), silu_mul(g1[3], u1[3], c1, c2));
;                 *(u32x4*)rowp = w; }
	v_mul_f32_e32 v161, v157, v161
	v_mul_f32_e32 v162, v157, v162
	v_mul_f32_e32 v163, v157, v163
	v_mul_f32_e32 v164, v157, v164
	v_mul_f32_e32 v0, v157, v0
	v_mul_f32_e32 v94, v90, v158
	v_mul_f32_e32 v95, v91, v159
	v_mul_f32_e32 v96, v92, v160
	v_mul_f32_e32 v97, v93, v161
	v_mul_f32_e32 v86, v82, v162
	v_mul_f32_e32 v87, v83, v163
	v_mul_f32_e32 v88, v84, v164
	v_mul_f32_e32 v89, v85, v0
	v_cvt_pk_bf16_f32 v90, v94, v95
	v_cvt_pk_bf16_f32 v91, v96, v97
	v_cvt_pk_bf16_f32 v92, v86, v87
	v_cvt_pk_bf16_f32 v93, v88, v89
	s_mov_b64 s[100:101], 0x2c000
	v_lshl_add_u64 v[150:151], v[148:149], 0, s[100:101]
	global_store_dwordx4 v[150:151], v[90:93], off
	v_mul_f32_e32 v156, 0xbfb8aa3b, v237
	v_mul_f32_e32 v157, v237, v237
	v_mul_f32_e32 v158, v78, v156
	v_mul_f32_e32 v159, v79, v156
	v_mul_f32_e32 v160, v80, v156
	v_mul_f32_e32 v161, v81, v156
	v_mul_f32_e32 v162, v70, v156
	v_mul_f32_e32 v163, v71, v156
	v_mul_f32_e32 v164, v72, v156
	v_mul_f32_e32 v0, v73, v156
	v_exp_f32_e32 v158, v158
	v_exp_f32_e32 v159, v159
	v_exp_f32_e32 v160, v160
	v_exp_f32_e32 v161, v161
	v_exp_f32_e32 v162, v162
	v_exp_f32_e32 v163, v163
	v_exp_f32_e32 v164, v164
	v_exp_f32_e32 v0, v0
	v_mul_f32_e32 v74, v78, v74
	v_mul_f32_e32 v75, v79, v75
	v_mul_f32_e32 v76, v80, v76
	v_mul_f32_e32 v77, v81, v77
	v_mul_f32_e32 v66, v70, v66
	v_mul_f32_e32 v67, v71, v67
	v_mul_f32_e32 v68, v72, v68
	v_mul_f32_e32 v69, v73, v69
	v_add_f32_e32 v158, 1.0, v158
	v_add_f32_e32 v159, 1.0, v159
	v_add_f32_e32 v160, 1.0, v160
	v_add_f32_e32 v161, 1.0, v161
	v_add_f32_e32 v162, 1.0, v162
	v_add_f32_e32 v163, 1.0, v163
	v_add_f32_e32 v164, 1.0, v164
	v_add_f32_e32 v0, 1.0, v0
	v_rcp_f32_e32 v158, v158
	v_rcp_f32_e32 v159, v159
	v_rcp_f32_e32 v160, v160
	v_rcp_f32_e32 v161, v161
	v_rcp_f32_e32 v162, v162
	v_rcp_f32_e32 v163, v163
	v_rcp_f32_e32 v164, v164
	v_rcp_f32_e32 v0, v0
	v_mul_f32_e32 v158, v157, v158
	v_mul_f32_e32 v159, v157, v159
	v_mul_f32_e32 v160, v157, v160
	v_mul_f32_e32 v161, v157, v161
	v_mul_f32_e32 v162, v157, v162
	v_mul_f32_e32 v163, v157, v163
	v_mul_f32_e32 v164, v157, v164
	v_mul_f32_e32 v0, v157, v0
	v_mul_f32_e32 v78, v74, v158
	v_mul_f32_e32 v79, v75, v159
	v_mul_f32_e32 v80, v76, v160
	v_mul_f32_e32 v81, v77, v161
	v_mul_f32_e32 v70, v66, v162
	v_mul_f32_e32 v71, v67, v163
	v_mul_f32_e32 v72, v68, v164
	v_mul_f32_e32 v73, v69, v0
	v_cvt_pk_bf16_f32 v74, v78, v79
	v_cvt_pk_bf16_f32 v75, v80, v81
	v_cvt_pk_bf16_f32 v76, v70, v71
	v_cvt_pk_bf16_f32 v77, v72, v73
	s_mov_b64 s[100:101], 0x42000
	v_lshl_add_u64 v[150:151], v[148:149], 0, s[100:101]
	global_store_dwordx4 v[150:151], v[74:77], off
	v_mul_f32_e32 v156, 0xbfb8aa3b, v245
	v_mul_f32_e32 v157, v245, v245
	v_mul_f32_e32 v158, v62, v156
	v_mul_f32_e32 v159, v63, v156
	v_mul_f32_e32 v160, v64, v156
	v_mul_f32_e32 v161, v65, v156
	v_mul_f32_e32 v162, v54, v156
	v_mul_f32_e32 v163, v55, v156
	v_mul_f32_e32 v164, v56, v156
	v_mul_f32_e32 v0, v57, v156
	v_exp_f32_e32 v158, v158
	v_exp_f32_e32 v159, v159
	v_exp_f32_e32 v160, v160
	v_exp_f32_e32 v161, v161
	v_exp_f32_e32 v162, v162
	v_exp_f32_e32 v163, v163
	v_exp_f32_e32 v164, v164
	v_exp_f32_e32 v0, v0
	v_mul_f32_e32 v58, v62, v58
	v_mul_f32_e32 v59, v63, v59
	v_mul_f32_e32 v60, v64, v60
	v_mul_f32_e32 v61, v65, v61
	v_mul_f32_e32 v50, v54, v50
	v_mul_f32_e32 v51, v55, v51
	v_mul_f32_e32 v52, v56, v52
	v_mul_f32_e32 v53, v57, v53
	v_add_f32_e32 v158, 1.0, v158
	v_add_f32_e32 v159, 1.0, v159
	v_add_f32_e32 v160, 1.0, v160
	v_add_f32_e32 v161, 1.0, v161
	v_add_f32_e32 v162, 1.0, v162
	v_add_f32_e32 v163, 1.0, v163
	v_add_f32_e32 v164, 1.0, v164
	v_add_f32_e32 v0, 1.0, v0
	v_rcp_f32_e32 v158, v158
	v_rcp_f32_e32 v159, v159
	v_rcp_f32_e32 v160, v160
	v_rcp_f32_e32 v161, v161
	v_rcp_f32_e32 v162, v162
	v_rcp_f32_e32 v163, v163
	v_rcp_f32_e32 v164, v164
	v_rcp_f32_e32 v0, v0
	v_mul_f32_e32 v158, v157, v158
	v_mul_f32_e32 v159, v157, v159
	v_mul_f32_e32 v160, v157, v160
	v_mul_f32_e32 v161, v157, v161
	v_mul_f32_e32 v162, v157, v162
	v_mul_f32_e32 v163, v157, v163
	v_mul_f32_e32 v164, v157, v164
	v_mul_f32_e32 v0, v157, v0
	v_mul_f32_e32 v62, v58, v158
	v_mul_f32_e32 v63, v59, v159
	v_mul_f32_e32 v64, v60, v160
	v_mul_f32_e32 v65, v61, v161
	v_mul_f32_e32 v54, v50, v162
	v_mul_f32_e32 v55, v51, v163
	v_mul_f32_e32 v56, v52, v164
	v_mul_f32_e32 v57, v53, v0
	v_cvt_pk_bf16_f32 v58, v62, v63
	v_cvt_pk_bf16_f32 v59, v64, v65
	v_cvt_pk_bf16_f32 v60, v54, v55
	v_cvt_pk_bf16_f32 v61, v56, v57
	s_mov_b64 s[100:101], 0xb0000
	v_lshl_add_u64 v[150:151], v[148:149], 0, s[100:101]
	global_store_dwordx4 v[150:151], v[58:61], off
	v_mul_f32_e32 v156, 0xbfb8aa3b, v247
	v_mul_f32_e32 v157, v247, v247
	v_mul_f32_e32 v158, v46, v156
	v_mul_f32_e32 v159, v47, v156
	v_mul_f32_e32 v160, v48, v156
	v_mul_f32_e32 v161, v49, v156
	v_mul_f32_e32 v162, v38, v156
	v_mul_f32_e32 v163, v39, v156
	v_mul_f32_e32 v164, v40, v156
	v_mul_f32_e32 v0, v41, v156
	v_exp_f32_e32 v158, v158
	v_exp_f32_e32 v159, v159
	v_exp_f32_e32 v160, v160
	v_exp_f32_e32 v161, v161
	v_exp_f32_e32 v162, v162
	v_exp_f32_e32 v163, v163
	v_exp_f32_e32 v164, v164
	v_exp_f32_e32 v0, v0
	v_mul_f32_e32 v42, v46, v42
	v_mul_f32_e32 v43, v47, v43
	v_mul_f32_e32 v44, v48, v44
	v_mul_f32_e32 v45, v49, v45
	v_mul_f32_e32 v34, v38, v34
	v_mul_f32_e32 v35, v39, v35
	v_mul_f32_e32 v36, v40, v36
; __device__ __forceinline__ unsigned cvt_pk_bf16(float lo, float hi) { unsigned r; asm volatile("v_cvt_pk_bf16_f32 %0, %1, %2" : "=v"(r) : "v"(lo), "v"(hi)); return r; }
; __device__ __forceinline__ float silu_mul(float g, float u, float c1, float c2) { const float e = __builtin_amdgcn_exp2f(g * c1); return (g * u) * (c2 * __builtin_amdgcn_rcpf(1.0f + e)); }
;     __device__ __forceinline__ void operator()(const f32x4 (&acc)[2][2][4][2], const Unit& u, int wr, int wc, int fr, int fq) const {
;     ...
;             for (int m = 0; m < 4; ++m) { bf16_t* rowp = O + (size_t)(row0 + ai * HALF + m * 16) * ldc + col0;
;                 const float rs = rsv[ai][m], c1 = rs * -1.4426950408889634f, c2 = rs * rs; const f32x4 g0 = acc[ai][0][m][0], g1 = acc[ai][0][m][1], u0 = acc[ai][1][m][0], u1 = acc[ai][1][m][1];
;                 u32x4 w; w.x = cvt_pk_bf16(silu_mul(g0[0], u0[0], c1, c2), silu_mul(g0[1], u0[1], c1, c2)); w.y = cvt_pk_bf16(silu_mul(g0[2], u0[2], c1, c2), silu_mul(g0[3], u0[3], c1, c2));
;                 w.z = cvt_pk_bf16(silu_mul(g1[0], u1[0], c1, c2), silu_mul(g1[1], u1[1], c1, c2)); w.w = cvt_pk_bf16(silu_mul(g1[2], u1[2], c1, c2), silu_mul(g1[3], u1[3], c1, c2));
;                 *(u32x4*)rowp = w; }
	v_mul_f32_e32 v37, v41, v37
	v_add_f32_e32 v158, 1.0, v158
	v_add_f32_e32 v159, 1.0, v159
	v_add_f32_e32 v160, 1.0, v160
	v_add_f32_e32 v161, 1.0, v161
	v_add_f32_e32 v162, 1.0, v162
	v_add_f32_e32 v163, 1.0, v163
	v_add_f32_e32 v164, 1.0, v164
	v_add_f32_e32 v0, 1.0, v0
	v_rcp_f32_e32 v158, v158
	v_rcp_f32_e32 v159, v159
	v_rcp_f32_e32 v160, v160
	v_rcp_f32_e32 v161, v161
	v_rcp_f32_e32 v162, v162
	v_rcp_f32_e32 v163, v163
	v_rcp_f32_e32 v164, v164
	v_rcp_f32_e32 v0, v0
	v_mul_f32_e32 v158, v157, v158
	v_mul_f32_e32 v159, v157, v159
	v_mul_f32_e32 v160, v157, v160
	v_mul_f32_e32 v161, v157, v161
	v_mul_f32_e32 v162, v157, v162
	v_mul_f32_e32 v163, v157, v163
	v_mul_f32_e32 v164, v157, v164
	v_mul_f32_e32 v0, v157, v0
	v_mul_f32_e32 v46, v42, v158
	v_mul_f32_e32 v47, v43, v159
	v_mul_f32_e32 v48, v44, v160
	v_mul_f32_e32 v49, v45, v161
	v_mul_f32_e32 v38, v34, v162
	v_mul_f32_e32 v39, v35, v163
	v_mul_f32_e32 v40, v36, v164
	v_mul_f32_e32 v41, v37, v0
	v_cvt_pk_bf16_f32 v42, v46, v47
	v_cvt_pk_bf16_f32 v43, v48, v49
	v_cvt_pk_bf16_f32 v44, v38, v39
	v_cvt_pk_bf16_f32 v45, v40, v41
	s_mov_b64 s[100:101], 0xc6000
	v_lshl_add_u64 v[150:151], v[148:149], 0, s[100:101]
	global_store_dwordx4 v[150:151], v[42:45], off
	v_mul_f32_e32 v156, 0xbfb8aa3b, v252
	v_mul_f32_e32 v157, v252, v252
	v_mul_f32_e32 v158, v30, v156
	v_mul_f32_e32 v159, v31, v156
	v_mul_f32_e32 v160, v32, v156
	v_mul_f32_e32 v161, v33, v156
	v_mul_f32_e32 v162, v22, v156
	v_mul_f32_e32 v163, v23, v156
	v_mul_f32_e32 v164, v24, v156
	v_mul_f32_e32 v0, v25, v156
	v_exp_f32_e32 v158, v158
	v_exp_f32_e32 v159, v159
	v_exp_f32_e32 v160, v160
	v_exp_f32_e32 v161, v161
	v_exp_f32_e32 v162, v162
	v_exp_f32_e32 v163, v163
	v_exp_f32_e32 v164, v164
	v_exp_f32_e32 v0, v0
	v_mul_f32_e32 v26, v30, v26
	v_mul_f32_e32 v27, v31, v27
	v_mul_f32_e32 v28, v32, v28
	v_mul_f32_e32 v29, v33, v29
	v_mul_f32_e32 v18, v22, v18
	v_mul_f32_e32 v19, v23, v19
	v_mul_f32_e32 v20, v24, v20
	v_mul_f32_e32 v21, v25, v21
	v_add_f32_e32 v158, 1.0, v158
	v_add_f32_e32 v159, 1.0, v159
	v_add_f32_e32 v160, 1.0, v160
	v_add_f32_e32 v161, 1.0, v161
	v_add_f32_e32 v162, 1.0, v162
	v_add_f32_e32 v163, 1.0, v163
	v_add_f32_e32 v164, 1.0, v164
	v_add_f32_e32 v0, 1.0, v0
	v_rcp_f32_e32 v158, v158
	v_rcp_f32_e32 v159, v159
	v_rcp_f32_e32 v160, v160
	v_rcp_f32_e32 v161, v161
	v_rcp_f32_e32 v162, v162
	v_rcp_f32_e32 v163, v163
	v_rcp_f32_e32 v164, v164
	v_rcp_f32_e32 v0, v0
	v_mul_f32_e32 v158, v157, v158
	v_mul_f32_e32 v159, v157, v159
	v_mul_f32_e32 v160, v157, v160
	v_mul_f32_e32 v161, v157, v161
	v_mul_f32_e32 v162, v157, v162
	v_mul_f32_e32 v163, v157, v163
	v_mul_f32_e32 v164, v157, v164
	v_mul_f32_e32 v0, v157, v0
	v_mul_f32_e32 v30, v26, v158
	v_mul_f32_e32 v31, v27, v159
	v_mul_f32_e32 v32, v28, v160
	v_mul_f32_e32 v33, v29, v161
	v_mul_f32_e32 v22, v18, v162
	v_mul_f32_e32 v23, v19, v163
	v_mul_f32_e32 v24, v20, v164
	v_mul_f32_e32 v25, v21, v0
	v_cvt_pk_bf16_f32 v26, v30, v31
	v_cvt_pk_bf16_f32 v27, v32, v33
	v_cvt_pk_bf16_f32 v28, v22, v23
	v_cvt_pk_bf16_f32 v29, v24, v25
	s_mov_b64 s[100:101], 0xdc000
	v_lshl_add_u64 v[150:151], v[148:149], 0, s[100:101]
	global_store_dwordx4 v[150:151], v[26:29], off
	v_mul_f32_e32 v156, 0xbfb8aa3b, v253
	v_mul_f32_e32 v157, v253, v253
	v_mul_f32_e32 v158, v14, v156
	v_mul_f32_e32 v159, v15, v156
	v_mul_f32_e32 v160, v16, v156
	v_mul_f32_e32 v161, v17, v156
	v_mul_f32_e32 v162, v6, v156
	v_mul_f32_e32 v163, v7, v156
	v_mul_f32_e32 v164, v8, v156
	v_mul_f32_e32 v0, v9, v156
	v_exp_f32_e32 v158, v158
	v_exp_f32_e32 v159, v159
	v_exp_f32_e32 v160, v160
	v_exp_f32_e32 v161, v161
	v_exp_f32_e32 v162, v162
	v_exp_f32_e32 v163, v163
	v_exp_f32_e32 v164, v164
	v_exp_f32_e32 v0, v0
	v_mul_f32_e32 v10, v14, v10
	v_mul_f32_e32 v11, v15, v11
	v_mul_f32_e32 v12, v16, v12
	v_mul_f32_e32 v13, v17, v13
	v_mul_f32_e32 v2, v6, v2
	v_mul_f32_e32 v3, v7, v3
	v_mul_f32_e32 v4, v8, v4
	v_mul_f32_e32 v5, v9, v5
	v_add_f32_e32 v158, 1.0, v158
	v_add_f32_e32 v159, 1.0, v159
	v_add_f32_e32 v160, 1.0, v160
	v_add_f32_e32 v161, 1.0, v161
	v_add_f32_e32 v162, 1.0, v162
	v_add_f32_e32 v163, 1.0, v163
	v_add_f32_e32 v164, 1.0, v164
	v_add_f32_e32 v0, 1.0, v0
	v_rcp_f32_e32 v158, v158
	v_rcp_f32_e32 v159, v159
	v_rcp_f32_e32 v160, v160
	v_rcp_f32_e32 v161, v161
	v_rcp_f32_e32 v162, v162
	v_rcp_f32_e32 v163, v163
	v_rcp_f32_e32 v164, v164
	v_rcp_f32_e32 v0, v0
	v_mul_f32_e32 v158, v157, v158
	v_mul_f32_e32 v159, v157, v159
	v_mul_f32_e32 v160, v157, v160
	v_mul_f32_e32 v161, v157, v161
	v_mul_f32_e32 v162, v157, v162
	v_mul_f32_e32 v163, v157, v163
	v_mul_f32_e32 v164, v157, v164
	v_mul_f32_e32 v0, v157, v0
	v_mul_f32_e32 v14, v10, v158
	v_mul_f32_e32 v15, v11, v159
	v_mul_f32_e32 v16, v12, v160
	v_mul_f32_e32 v17, v13, v161
	v_mul_f32_e32 v6, v2, v162
	v_mul_f32_e32 v7, v3, v163
	v_mul_f32_e32 v8, v4, v164
	v_mul_f32_e32 v9, v5, v0
	v_cvt_pk_bf16_f32 v10, v14, v15
	v_cvt_pk_bf16_f32 v11, v16, v17
	v_cvt_pk_bf16_f32 v12, v6, v7
	v_cvt_pk_bf16_f32 v13, v8, v9
	s_mov_b64 s[100:101], 0xf2000
	v_lshl_add_u64 v[150:151], v[148:149], 0, s[100:101]
	global_store_dwordx4 v[150:151], v[10:13], off
	s_mov_b64 s[30:31], -1
	s_andn2_b64 vcc, exec, s[36:37]
	s_cbranch_vccnz .LBB0_787
	s_andn2_b64 vcc, exec, s[4:5]
	s_cbranch_vccnz .LBB0_786
	s_barrier
	s_branch .LBB0_786

; __global__ void __launch_bounds__(NWAVES * 64, 2) mega_fwd(Args args) {
	.amdhsa_kernel _Z8mega_fwd4Args
		.amdhsa_group_segment_fixed_size 0
		.amdhsa_private_segment_fixed_size 0
		.amdhsa_kernarg_size 440
		.amdhsa_user_sgpr_count 2
		.amdhsa_user_sgpr_dispatch_ptr 0
		.amdhsa_user_sgpr_queue_ptr 0
		.amdhsa_user_sgpr_kernarg_segment_ptr 1
		.amdhsa_user_sgpr_dispatch_id 0
		.amdhsa_user_sgpr_kernarg_preload_length 0
		.amdhsa_user_sgpr_kernarg_preload_offset 0
		.amdhsa_user_sgpr_private_segment_size 0
		.amdhsa_uses_dynamic_stack 0
		.amdhsa_enable_private_segment 0
		.amdhsa_system_sgpr_workgroup_id_x 1
		.amdhsa_system_sgpr_workgroup_id_y 0
		.amdhsa_system_sgpr_workgroup_id_z 0
		.amdhsa_system_sgpr_workgroup_info 0
		.amdhsa_system_vgpr_workitem_id 2
		.amdhsa_next_free_vgpr 256
		.amdhsa_next_free_sgpr 102
		.amdhsa_accum_offset 256
		.amdhsa_reserve_vcc 1
		.amdhsa_float_round_mode_32 0
		.amdhsa_float_round_mode_16_64 0
		.amdhsa_float_denorm_mode_32 3
		.amdhsa_float_denorm_mode_16_64 3
		.amdhsa_dx10_clamp 1
		.amdhsa_ieee_mode 1
		.amdhsa_fp16_overflow 0
		.amdhsa_tg_split 0
		.amdhsa_exception_fp_ieee_invalid_op 0
		.amdhsa_exception_fp_denorm_src 0
		.amdhsa_exception_fp_ieee_div_zero 0
		.amdhsa_exception_fp_ieee_overflow 0
		.amdhsa_exception_fp_ieee_underflow 0
		.amdhsa_exception_fp_ieee_inexact 0
		.amdhsa_exception_int_div_zero 0
	.end_amdhsa_kernel

; __global__ void __launch_bounds__(NWAVES * 64, 2) mega_fwd(Args args) {
amdhsa.kernels:
  - .agpr_count:     0
    .args:
      - .offset:         0
        .size:           184
        .value_kind:     by_value
      - .offset:         184
        .size:           4
        .value_kind:     hidden_block_count_x
      - .offset:         188
        .size:           4
        .value_kind:     hidden_block_count_y
      - .offset:         192
        .size:           4
        .value_kind:     hidden_block_count_z
      - .offset:         196
        .size:           2
        .value_kind:     hidden_group_size_x
      - .offset:         198
        .size:           2
        .value_kind:     hidden_group_size_y
      - .offset:         200
        .size:           2
        .value_kind:     hidden_group_size_z
      - .offset:         202
        .size:           2
        .value_kind:     hidden_remainder_x
      - .offset:         204
        .size:           2
        .value_kind:     hidden_remainder_y
      - .offset:         206
        .size:           2
        .value_kind:     hidden_remainder_z
      - .offset:         224
        .size:           8
        .value_kind:     hidden_global_offset_x
      - .offset:         232
        .size:           8
        .value_kind:     hidden_global_offset_y
      - .offset:         240
        .size:           8
        .value_kind:     hidden_global_offset_z
      - .offset:         248
        .size:           2
        .value_kind:     hidden_grid_dims
      - .offset:         272
        .size:           8
        .value_kind:     hidden_multigrid_sync_arg
      - .offset:         304
        .size:           4
        .value_kind:     hidden_dynamic_lds_size
    .group_segment_fixed_size: 0
    .kernarg_segment_align: 8
    .kernarg_segment_size: 440
    .language:       OpenCL C
    .language_version:
      - 2
      - 0
    .max_flat_workgroup_size: 512
    .name:           _Z8mega_fwd4Args
    .private_segment_fixed_size: 0
    .sgpr_count:     108
    .sgpr_spill_count: 88
    .symbol:         _Z8mega_fwd4Args.kd
    .uniform_work_group_size: 1
    .uses_dynamic_stack: false
    .vgpr_count:     256
    .vgpr_spill_count: 0
    .wavefront_size: 64
